# nt hint on the streaming act / q,k,v / final f32 output stores; snake MFMA order
# baseline (speedup 1.0000x reference)
;     __device__ __forceinline__ void operator()(const f32x4 (&acc)[2][2][4][2], const Unit& u, int wr, int wc, int fr, int fq, const LAS float* rt) const {
;     ...
;             for (int m = 0; m < 4; ++m) {
;                 const int row = row0 + ai * 128 + m * 16; const float rs = rt ? rt[wr * 64 + fr + ai * 128 + m * 16] : row_rstd(ssq, row);
;                 f32x4 v[2][2]; float ss = 0.f;
; #pragma unroll
;                 for (int bj = 0; bj < 2; ++bj)
; #pragma unroll
;                     for (int n = 0; n < 2; ++n) { v[bj][n] = acc[ai][bj][m][n] * rs; const f32x4 q = v[bj][n] * v[bj][n]; ss += (q[0] + q[1]) + (q[2] + q[3]); }
;                 ss = sum_x16_x32(ss);
;                 const float sc = kind < 2 ? __builtin_amdgcn_rsqf(ss * (1.f / 64.f) + RMS_EPS) : 1.f;
;                 const int tt = row & (SEQ - 1); const int prow = (row & ~(SEQ - 1)) + (tt & ((1 << rsh) - 1)) * (SEQ >> rsh) + (tt >> rsh);
; #pragma unroll
;                 for (int bj = 0; bj < 2; ++bj)
;                     gst<u32x4>((kind == 0 ? Oq : Okv + (size_t)(kind - 1) * 16 * M * 64) + ((size_t)(4 * (u.pn & 3) + wc) * M + prow) * 64 + 32 * bj + 8 * fq, pack8(v[bj][0] * sc * gv[bj][0], v[bj][1] * sc * gv[bj][1]));
.LBB0_178:
	s_waitcnt lgkmcnt(0)
	v_pk_mul_f32 v[128:129], v[128:129], v[160:161] op_sel_hi:[1,0]
	v_pk_mul_f32 v[126:127], v[126:127], v[160:161] op_sel_hi:[1,0]
	v_pk_mul_f32 v[164:165], v[128:129], v[128:129]
	v_pk_mul_f32 v[166:167], v[126:127], v[126:127]
	v_pk_mul_f32 v[120:121], v[120:121], v[160:161] op_sel_hi:[1,0]
	v_pk_mov_b32 v[168:169], v[166:167], v[164:165] op_sel:[1,0]
	v_mov_b32_e32 v167, v165
	v_pk_mul_f32 v[118:119], v[118:119], v[160:161] op_sel_hi:[1,0]
	v_pk_add_f32 v[164:165], v[168:169], v[166:167]
	v_pk_mul_f32 v[166:167], v[120:121], v[120:121]
	v_pk_mul_f32 v[168:169], v[118:119], v[118:119]
	v_pk_mul_f32 v[124:125], v[124:125], v[160:161] op_sel_hi:[1,0]
	v_pk_mov_b32 v[170:171], v[168:169], v[166:167] op_sel:[1,0]
	v_mov_b32_e32 v169, v167
	v_pk_add_f32 v[166:167], v[170:171], v[168:169]
	v_pk_mul_f32 v[122:123], v[122:123], v[160:161] op_sel_hi:[1,0]
	v_pk_mul_f32 v[172:173], v[116:117], v[160:161] op_sel_hi:[1,0]
	v_pk_mul_f32 v[174:175], v[114:115], v[160:161] op_sel_hi:[1,0]
	v_pk_add_f32 v[164:165], v[164:165], v[164:165] op_sel_hi:[0,1]
	v_pk_add_f32 v[166:167], v[166:167], v[166:167] op_sel_hi:[0,1]
	v_pk_mul_f32 v[168:169], v[124:125], v[124:125]
	v_pk_mul_f32 v[170:171], v[122:123], v[122:123]
	v_pk_mul_f32 v[114:115], v[172:173], v[172:173]
	v_pk_mul_f32 v[116:117], v[174:175], v[174:175]
	v_add_f32_e32 v171, v170, v171
	v_add_f32_e32 v169, v168, v169
	v_mov_b32_e32 v170, v116
	v_mov_b32_e32 v168, v117
	v_mov_b32_e32 v164, v114
	v_mov_b32_e32 v166, v115
	v_pk_add_f32 v[116:117], v[170:171], v[168:169]
	v_pk_add_f32 v[114:115], v[164:165], v[166:167]
	s_lshl_b32 s3, s4, 2
	v_pk_add_f32 v[114:115], v[116:117], v[114:115]
	s_and_b32 s3, s3, 12
	v_add_f32_e32 v114, v114, v115
	v_mov_b32_e32 v115, v114
	s_nop 1
	v_permlane16_swap_b32 v114, v115
	s_nop 1
	v_readlane_b32 s4, v255, 44
	v_add_f32_e32 v114, v114, v115
	v_mov_b32_e32 v115, v114
	s_nop 1
	v_permlane32_swap_b32 v114, v115
	s_nop 1
	s_or_b32 s3, s3, s4
	v_add_f32_e32 v114, v114, v115
	v_fmamk_f32 v114, v114, 0x3c800000, v251
	v_rsq_f32_e32 v114, v114
	s_ashr_i32 s25, s24, 31
	s_lshl_b32 s4, s3, 15
	s_lshl_b64 s[8:9], s[24:25], 26
	s_and_b32 s26, s2, 0xffffe000
	v_readlane_b32 s2, v255, 27
	v_readlane_b32 s3, v255, 28
	s_add_u32 s2, s2, s8
	v_cndmask_b32_e64 v160, 1.0, v114, s[42:43]
	v_and_b32_e32 v114, 0x1fcf, v158
	s_addc_u32 s3, s3, s9
	v_lshrrev_b32_e32 v114, s58, v114
	s_add_u32 s2, s2, 0xfc000000
	v_bitop3_b32 v115, v158, s99, v252 bitop3:0x80
	v_or_b32_e32 v114, s26, v114
	s_addc_u32 s3, s3, -1
	v_mad_u32_u24 v114, v115, s59, v114
	s_and_b64 s[0:1], s[0:1], exec
	v_ashrrev_i32_e32 v115, 31, v114
	v_readlane_b32 s0, v255, 25
	v_lshl_add_u64 v[114:115], v[114:115], 0, s[4:5]
	v_readlane_b32 s1, v255, 26
	v_lshlrev_b64 v[114:115], 7, v[114:115]
	s_cselect_b32 s1, s1, s3
	s_cselect_b32 s0, s0, s2
	v_lshl_add_u64 v[116:117], s[0:1], 0, v[114:115]
	v_lshlrev_b32_e32 v114, 1, v163
	v_mov_b32_e32 v115, v96
	v_lshl_add_u64 v[164:165], v[116:117], 0, v[114:115]
	v_pk_mul_f32 v[116:117], v[126:127], v[160:161] op_sel_hi:[1,0]
	v_pk_mul_f32 v[118:119], v[118:119], v[160:161] op_sel_hi:[1,0]
	v_pk_mul_f32 v[126:127], v[128:129], v[160:161] op_sel_hi:[1,0]
	v_pk_mul_f32 v[116:117], v[144:145], v[116:117]
	v_pk_mul_f32 v[120:121], v[120:121], v[160:161] op_sel_hi:[1,0]
	v_pk_mul_f32 v[118:119], v[142:143], v[118:119]
	v_pk_mul_f32 v[126:127], v[146:147], v[126:127]
	v_pk_mul_f32 v[120:121], v[148:149], v[120:121]
	v_cvt_pk_bf16_f32 v116, v116, v117
	v_cvt_pk_bf16_f32 v117, v126, v127
	v_cvt_pk_bf16_f32 v118, v118, v119
	v_cndmask_b32_e64 v115, 0, 1, s[50:51]
	v_cvt_pk_bf16_f32 v119, v120, v121
	global_store_dwordx4 v[164:165], v[116:119], off nt
	v_pk_mul_f32 v[120:121], v[174:175], v[160:161] op_sel_hi:[1,0]
	v_cmp_ne_u32_e64 s[44:45], 1, v115
	v_pk_mul_f32 v[116:117], v[122:123], v[160:161] op_sel_hi:[1,0]
	v_pk_mul_f32 v[118:119], v[124:125], v[160:161] op_sel_hi:[1,0]
	v_pk_mul_f32 v[116:117], v[152:153], v[116:117]
	v_pk_mul_f32 v[118:119], v[154:155], v[118:119]
	v_pk_mul_f32 v[122:123], v[172:173], v[160:161] op_sel_hi:[1,0]
	v_pk_mul_f32 v[120:121], v[150:151], v[120:121]
	v_cvt_pk_bf16_f32 v116, v116, v117
	v_cvt_pk_bf16_f32 v117, v118, v119
	s_andn2_b64 vcc, exec, s[50:51]
	v_cvt_pk_bf16_f32 v118, v120, v121
	s_mov_b64 s[24:25], -1
	v_pk_mul_f32 v[122:123], v[156:157], v[122:123]
	s_nop 0
	v_cvt_pk_bf16_f32 v119, v122, v123
	global_store_dwordx4 v[164:165], v[116:119], off offset:64 nt
	s_cbranch_vccnz .LBB0_180
	ds_read_b32 v118, v162 offset:64
	s_mov_b64 s[24:25], 0

;     __device__ __forceinline__ void operator()(const f32x4 (&acc)[2][2][4][2], const Unit& u, int wr, int wc, int fr, int fq, const LAS float* rt) const {
;     ...
;             for (int m = 0; m < 4; ++m) {
;                 const int row = row0 + ai * 128 + m * 16; const float rs = rt ? rt[wr * 64 + fr + ai * 128 + m * 16] : row_rstd(ssq, row);
;                 f32x4 v[2][2]; float ss = 0.f;
; #pragma unroll
;                 for (int bj = 0; bj < 2; ++bj)
; #pragma unroll
;                     for (int n = 0; n < 2; ++n) { v[bj][n] = acc[ai][bj][m][n] * rs; const f32x4 q = v[bj][n] * v[bj][n]; ss += (q[0] + q[1]) + (q[2] + q[3]); }
;                 ss = sum_x16_x32(ss);
;                 const float sc = kind < 2 ? __builtin_amdgcn_rsqf(ss * (1.f / 64.f) + RMS_EPS) : 1.f;
;                 const int tt = row & (SEQ - 1); const int prow = (row & ~(SEQ - 1)) + (tt & ((1 << rsh) - 1)) * (SEQ >> rsh) + (tt >> rsh);
; #pragma unroll
;                 for (int bj = 0; bj < 2; ++bj)
;                     gst<u32x4>((kind == 0 ? Oq : Okv + (size_t)(kind - 1) * 16 * M * 64) + ((size_t)(4 * (u.pn & 3) + wc) * M + prow) * 64 + 32 * bj + 8 * fq, pack8(v[bj][0] * sc * gv[bj][0], v[bj][1] * sc * gv[bj][1]));
.LBB0_182:
	s_waitcnt lgkmcnt(0)
	v_pk_mul_f32 v[112:113], v[112:113], v[118:119] op_sel_hi:[1,0]
	v_pk_mul_f32 v[110:111], v[110:111], v[118:119] op_sel_hi:[1,0]
	v_pk_mul_f32 v[120:121], v[112:113], v[112:113]
	v_pk_mul_f32 v[122:123], v[110:111], v[110:111]
	v_pk_mul_f32 v[104:105], v[104:105], v[118:119] op_sel_hi:[1,0]
	v_pk_mov_b32 v[124:125], v[122:123], v[120:121] op_sel:[1,0]
	v_mov_b32_e32 v123, v121
	v_pk_mul_f32 v[102:103], v[102:103], v[118:119] op_sel_hi:[1,0]
	v_pk_add_f32 v[120:121], v[124:125], v[122:123]
	v_pk_mul_f32 v[122:123], v[104:105], v[104:105]
	v_pk_mul_f32 v[124:125], v[102:103], v[102:103]
	v_pk_mul_f32 v[106:107], v[106:107], v[118:119] op_sel_hi:[1,0]
	v_pk_mov_b32 v[126:127], v[124:125], v[122:123] op_sel:[1,0]
	v_mov_b32_e32 v125, v123
	v_pk_add_f32 v[122:123], v[126:127], v[124:125]
	v_pk_mul_f32 v[126:127], v[106:107], v[106:107]
	v_pk_mul_f32 v[108:109], v[108:109], v[118:119] op_sel_hi:[1,0]
	v_add_f32_e32 v119, v126, v127
	v_pk_mul_f32 v[126:127], v[100:101], v[118:119] op_sel_hi:[1,0]
	v_pk_mul_f32 v[128:129], v[98:99], v[118:119] op_sel_hi:[1,0]
	v_pk_add_f32 v[120:121], v[120:121], v[120:121] op_sel_hi:[0,1]
	v_pk_add_f32 v[122:123], v[122:123], v[122:123] op_sel_hi:[0,1]
	v_pk_mul_f32 v[124:125], v[108:109], v[108:109]
	v_pk_mul_f32 v[98:99], v[126:127], v[126:127]
	v_pk_mul_f32 v[100:101], v[128:129], v[128:129]
	v_add_f32_e32 v125, v124, v125
	v_mov_b32_e32 v118, v100
	v_mov_b32_e32 v124, v101
	v_mov_b32_e32 v120, v98
	v_mov_b32_e32 v122, v99
	v_pk_add_f32 v[100:101], v[118:119], v[124:125]
	v_pk_add_f32 v[98:99], v[120:121], v[122:123]
	v_mov_b32_e32 v115, v96
	v_pk_add_f32 v[98:99], v[100:101], v[98:99]
	s_and_b64 vcc, exec, s[44:45]
	v_add_f32_e32 v98, v98, v99
	v_mov_b32_e32 v99, v98
	s_nop 1
	v_permlane16_swap_b32 v98, v99
	s_nop 1
	s_mov_b64 s[24:25], -1
	v_add_f32_e32 v98, v98, v99
	v_mov_b32_e32 v99, v98
	s_nop 1
	v_permlane32_swap_b32 v98, v99
	s_nop 1
	s_nop 0
	v_add_f32_e32 v98, v98, v99
	v_fmamk_f32 v98, v98, 0x3c800000, v251
	v_rsq_f32_e32 v98, v98
	v_mov_b32_e32 v99, 0x1fdf
	v_bitop3_b32 v99, v116, s99, v99 bitop3:0x80
	v_cndmask_b32_e64 v118, 1.0, v98, s[42:43]
	v_and_b32_e32 v98, 0x1fdf, v116
	v_lshrrev_b32_e32 v98, s58, v98
	v_or_b32_e32 v98, s26, v98
	v_mad_u32_u24 v98, v99, s59, v98
	v_ashrrev_i32_e32 v99, 31, v98
	v_lshl_add_u64 v[98:99], v[98:99], 0, s[4:5]
	v_lshlrev_b64 v[98:99], 7, v[98:99]
	v_lshl_add_u64 v[98:99], s[0:1], 0, v[98:99]
	v_lshl_add_u64 v[116:117], v[98:99], 0, v[114:115]
	v_pk_mul_f32 v[98:99], v[110:111], v[118:119] op_sel_hi:[1,0]
	v_pk_mul_f32 v[100:101], v[112:113], v[118:119] op_sel_hi:[1,0]
	v_pk_mul_f32 v[98:99], v[144:145], v[98:99]
	v_pk_mul_f32 v[100:101], v[146:147], v[100:101]
	v_pk_mul_f32 v[102:103], v[102:103], v[118:119] op_sel_hi:[1,0]
	v_pk_mul_f32 v[104:105], v[104:105], v[118:119] op_sel_hi:[1,0]
	v_pk_mul_f32 v[102:103], v[142:143], v[102:103]
	v_pk_mul_f32 v[104:105], v[148:149], v[104:105]
	v_cvt_pk_bf16_f32 v98, v98, v99
	v_cvt_pk_bf16_f32 v99, v100, v101
	v_cvt_pk_bf16_f32 v100, v102, v103
	v_pk_mul_f32 v[102:103], v[128:129], v[118:119] op_sel_hi:[1,0]
	v_cvt_pk_bf16_f32 v101, v104, v105
	global_store_dwordx4 v[116:117], v[98:101], off nt
	v_pk_mul_f32 v[104:105], v[126:127], v[118:119] op_sel_hi:[1,0]
	v_pk_mul_f32 v[102:103], v[150:151], v[102:103]
	v_pk_mul_f32 v[98:99], v[106:107], v[118:119] op_sel_hi:[1,0]
	v_pk_mul_f32 v[100:101], v[108:109], v[118:119] op_sel_hi:[1,0]
	v_pk_mul_f32 v[98:99], v[152:153], v[98:99]
	v_pk_mul_f32 v[100:101], v[154:155], v[100:101]
	v_cvt_pk_bf16_f32 v98, v98, v99
	v_pk_mul_f32 v[104:105], v[156:157], v[104:105]
	v_cvt_pk_bf16_f32 v99, v100, v101
	v_cvt_pk_bf16_f32 v100, v102, v103
	s_nop 0
	v_cvt_pk_bf16_f32 v101, v104, v105
	global_store_dwordx4 v[116:117], v[98:101], off offset:64 nt
	s_cbranch_vccnz .LBB0_184
	ds_read_b32 v100, v162 offset:128
	s_mov_b64 s[24:25], 0

;     __device__ __forceinline__ void operator()(const f32x4 (&acc)[2][2][4][2], const Unit& u, int wr, int wc, int fr, int fq, const LAS float* rt) const {
;     ...
;             for (int m = 0; m < 4; ++m) {
;                 const int row = row0 + ai * 128 + m * 16; const float rs = rt ? rt[wr * 64 + fr + ai * 128 + m * 16] : row_rstd(ssq, row);
;                 f32x4 v[2][2]; float ss = 0.f;
; #pragma unroll
;                 for (int bj = 0; bj < 2; ++bj)
; #pragma unroll
;                     for (int n = 0; n < 2; ++n) { v[bj][n] = acc[ai][bj][m][n] * rs; const f32x4 q = v[bj][n] * v[bj][n]; ss += (q[0] + q[1]) + (q[2] + q[3]); }
;                 ss = sum_x16_x32(ss);
;                 const float sc = kind < 2 ? __builtin_amdgcn_rsqf(ss * (1.f / 64.f) + RMS_EPS) : 1.f;
;                 const int tt = row & (SEQ - 1); const int prow = (row & ~(SEQ - 1)) + (tt & ((1 << rsh) - 1)) * (SEQ >> rsh) + (tt >> rsh);
; #pragma unroll
;                 for (int bj = 0; bj < 2; ++bj)
;                     gst<u32x4>((kind == 0 ? Oq : Okv + (size_t)(kind - 1) * 16 * M * 64) + ((size_t)(4 * (u.pn & 3) + wc) * M + prow) * 64 + 32 * bj + 8 * fq, pack8(v[bj][0] * sc * gv[bj][0], v[bj][1] * sc * gv[bj][1]));
.LBB0_186:
	s_waitcnt lgkmcnt(0)
	v_pk_mul_f32 v[94:95], v[94:95], v[100:101] op_sel_hi:[1,0]
	v_pk_mul_f32 v[92:93], v[92:93], v[100:101] op_sel_hi:[1,0]
	v_pk_mul_f32 v[102:103], v[94:95], v[94:95]
	v_pk_mul_f32 v[104:105], v[92:93], v[92:93]
	v_pk_mul_f32 v[86:87], v[86:87], v[100:101] op_sel_hi:[1,0]
	v_pk_mov_b32 v[106:107], v[104:105], v[102:103] op_sel:[1,0]
	v_mov_b32_e32 v105, v103
	v_pk_mul_f32 v[84:85], v[84:85], v[100:101] op_sel_hi:[1,0]
	v_pk_add_f32 v[102:103], v[106:107], v[104:105]
	v_pk_mul_f32 v[104:105], v[86:87], v[86:87]
	v_pk_mul_f32 v[106:107], v[84:85], v[84:85]
	v_pk_mul_f32 v[88:89], v[88:89], v[100:101] op_sel_hi:[1,0]
	v_pk_mov_b32 v[108:109], v[106:107], v[104:105] op_sel:[1,0]
	v_mov_b32_e32 v107, v105
	v_pk_add_f32 v[104:105], v[108:109], v[106:107]
	v_pk_mul_f32 v[108:109], v[88:89], v[88:89]
	v_pk_mul_f32 v[90:91], v[90:91], v[100:101] op_sel_hi:[1,0]
	v_add_f32_e32 v101, v108, v109
	v_pk_mul_f32 v[108:109], v[82:83], v[100:101] op_sel_hi:[1,0]
	v_pk_mul_f32 v[110:111], v[80:81], v[100:101] op_sel_hi:[1,0]
	v_pk_add_f32 v[102:103], v[102:103], v[102:103] op_sel_hi:[0,1]
	v_pk_add_f32 v[104:105], v[104:105], v[104:105] op_sel_hi:[0,1]
	v_pk_mul_f32 v[106:107], v[90:91], v[90:91]
	v_pk_mul_f32 v[80:81], v[108:109], v[108:109]
	v_pk_mul_f32 v[82:83], v[110:111], v[110:111]
	v_add_f32_e32 v107, v106, v107
	v_mov_b32_e32 v100, v82
	v_mov_b32_e32 v106, v83
	v_mov_b32_e32 v102, v80
	v_mov_b32_e32 v104, v81
	v_pk_add_f32 v[82:83], v[100:101], v[106:107]
	v_pk_add_f32 v[80:81], v[102:103], v[104:105]
	v_mov_b32_e32 v115, v96
	v_pk_add_f32 v[80:81], v[82:83], v[80:81]
	s_and_b64 vcc, exec, s[44:45]
	v_add_f32_e32 v80, v80, v81
	v_mov_b32_e32 v81, v80
	s_nop 1
	v_permlane16_swap_b32 v80, v81
	s_nop 1
	s_mov_b64 s[24:25], -1
	v_add_f32_e32 v80, v80, v81
	v_mov_b32_e32 v81, v80
	s_nop 1
	v_permlane32_swap_b32 v80, v81
	s_nop 1
	s_nop 0
	v_add_f32_e32 v80, v80, v81
	v_fmamk_f32 v80, v80, 0x3c800000, v251
	v_rsq_f32_e32 v80, v80
	v_mov_b32_e32 v81, 0x1fef
	v_bitop3_b32 v81, v98, s99, v81 bitop3:0x80
	v_cndmask_b32_e64 v100, 1.0, v80, s[42:43]
	v_and_b32_e32 v80, 0x1fef, v98
	v_lshrrev_b32_e32 v80, s58, v80
	v_or_b32_e32 v80, s26, v80
	v_mad_u32_u24 v80, v81, s59, v80
	v_ashrrev_i32_e32 v81, 31, v80
	v_lshl_add_u64 v[80:81], v[80:81], 0, s[4:5]
	v_lshlrev_b64 v[80:81], 7, v[80:81]
	v_lshl_add_u64 v[80:81], s[0:1], 0, v[80:81]
	v_lshl_add_u64 v[98:99], v[80:81], 0, v[114:115]
	v_pk_mul_f32 v[80:81], v[92:93], v[100:101] op_sel_hi:[1,0]
	v_pk_mul_f32 v[82:83], v[94:95], v[100:101] op_sel_hi:[1,0]
	v_pk_mul_f32 v[80:81], v[144:145], v[80:81]
	v_pk_mul_f32 v[82:83], v[146:147], v[82:83]
	v_pk_mul_f32 v[84:85], v[84:85], v[100:101] op_sel_hi:[1,0]
	v_pk_mul_f32 v[86:87], v[86:87], v[100:101] op_sel_hi:[1,0]
	v_pk_mul_f32 v[84:85], v[142:143], v[84:85]
	v_pk_mul_f32 v[86:87], v[148:149], v[86:87]
	v_cvt_pk_bf16_f32 v80, v80, v81
	v_cvt_pk_bf16_f32 v81, v82, v83
	v_cvt_pk_bf16_f32 v82, v84, v85
	v_pk_mul_f32 v[84:85], v[110:111], v[100:101] op_sel_hi:[1,0]
	v_cvt_pk_bf16_f32 v83, v86, v87
	global_store_dwordx4 v[98:99], v[80:83], off nt
	v_pk_mul_f32 v[86:87], v[108:109], v[100:101] op_sel_hi:[1,0]
	v_pk_mul_f32 v[84:85], v[150:151], v[84:85]
	v_pk_mul_f32 v[80:81], v[88:89], v[100:101] op_sel_hi:[1,0]
	v_pk_mul_f32 v[82:83], v[90:91], v[100:101] op_sel_hi:[1,0]
	v_pk_mul_f32 v[80:81], v[152:153], v[80:81]
	v_pk_mul_f32 v[82:83], v[154:155], v[82:83]
	v_cvt_pk_bf16_f32 v80, v80, v81
	v_pk_mul_f32 v[86:87], v[156:157], v[86:87]
	v_cvt_pk_bf16_f32 v81, v82, v83
	v_cvt_pk_bf16_f32 v82, v84, v85
	s_nop 0
	v_cvt_pk_bf16_f32 v83, v86, v87
	global_store_dwordx4 v[98:99], v[80:83], off offset:64 nt
	s_cbranch_vccnz .LBB0_188
	ds_read_b32 v82, v162 offset:192
	s_mov_b64 s[24:25], 0

;     __device__ __forceinline__ void operator()(const f32x4 (&acc)[2][2][4][2], const Unit& u, int wr, int wc, int fr, int fq, const LAS float* rt) const {
;     ...
;             for (int m = 0; m < 4; ++m) {
;                 const int row = row0 + ai * 128 + m * 16; const float rs = rt ? rt[wr * 64 + fr + ai * 128 + m * 16] : row_rstd(ssq, row);
;                 f32x4 v[2][2]; float ss = 0.f;
; #pragma unroll
;                 for (int bj = 0; bj < 2; ++bj)
; #pragma unroll
;                     for (int n = 0; n < 2; ++n) { v[bj][n] = acc[ai][bj][m][n] * rs; const f32x4 q = v[bj][n] * v[bj][n]; ss += (q[0] + q[1]) + (q[2] + q[3]); }
;                 ss = sum_x16_x32(ss);
;                 const float sc = kind < 2 ? __builtin_amdgcn_rsqf(ss * (1.f / 64.f) + RMS_EPS) : 1.f;
;                 const int tt = row & (SEQ - 1); const int prow = (row & ~(SEQ - 1)) + (tt & ((1 << rsh) - 1)) * (SEQ >> rsh) + (tt >> rsh);
; #pragma unroll
;                 for (int bj = 0; bj < 2; ++bj)
;                     gst<u32x4>((kind == 0 ? Oq : Okv + (size_t)(kind - 1) * 16 * M * 64) + ((size_t)(4 * (u.pn & 3) + wc) * M + prow) * 64 + 32 * bj + 8 * fq, pack8(v[bj][0] * sc * gv[bj][0], v[bj][1] * sc * gv[bj][1]));
.LBB0_190:
	s_waitcnt lgkmcnt(0)
	v_pk_mul_f32 v[78:79], v[78:79], v[82:83] op_sel_hi:[1,0]
	v_pk_mul_f32 v[76:77], v[76:77], v[82:83] op_sel_hi:[1,0]
	v_pk_mul_f32 v[84:85], v[78:79], v[78:79]
	v_pk_mul_f32 v[86:87], v[76:77], v[76:77]
	v_pk_mul_f32 v[70:71], v[70:71], v[82:83] op_sel_hi:[1,0]
	v_pk_mov_b32 v[88:89], v[86:87], v[84:85] op_sel:[1,0]
	v_mov_b32_e32 v87, v85
	v_pk_mul_f32 v[68:69], v[68:69], v[82:83] op_sel_hi:[1,0]
	v_pk_add_f32 v[84:85], v[88:89], v[86:87]
	v_pk_mul_f32 v[86:87], v[70:71], v[70:71]
	v_pk_mul_f32 v[88:89], v[68:69], v[68:69]
	v_pk_mul_f32 v[72:73], v[72:73], v[82:83] op_sel_hi:[1,0]
	v_pk_mov_b32 v[90:91], v[88:89], v[86:87] op_sel:[1,0]
	v_mov_b32_e32 v89, v87
	v_pk_add_f32 v[86:87], v[90:91], v[88:89]
	v_pk_mul_f32 v[90:91], v[72:73], v[72:73]
	v_pk_mul_f32 v[74:75], v[74:75], v[82:83] op_sel_hi:[1,0]
	v_add_f32_e32 v83, v90, v91
	v_pk_mul_f32 v[90:91], v[66:67], v[82:83] op_sel_hi:[1,0]
	v_pk_mul_f32 v[92:93], v[64:65], v[82:83] op_sel_hi:[1,0]
	v_pk_add_f32 v[84:85], v[84:85], v[84:85] op_sel_hi:[0,1]
	v_pk_add_f32 v[86:87], v[86:87], v[86:87] op_sel_hi:[0,1]
	v_pk_mul_f32 v[88:89], v[74:75], v[74:75]
	v_pk_mul_f32 v[64:65], v[90:91], v[90:91]
	v_pk_mul_f32 v[66:67], v[92:93], v[92:93]
	v_add_f32_e32 v89, v88, v89
	v_mov_b32_e32 v82, v66
	v_mov_b32_e32 v88, v67
	v_mov_b32_e32 v84, v64
	v_mov_b32_e32 v86, v65
	v_pk_add_f32 v[66:67], v[82:83], v[88:89]
	v_pk_add_f32 v[64:65], v[84:85], v[86:87]
	v_mov_b32_e32 v115, v96
	v_pk_add_f32 v[64:65], v[66:67], v[64:65]
	s_and_b64 vcc, exec, s[44:45]
	v_add_f32_e32 v64, v64, v65
	v_mov_b32_e32 v65, v64
	s_nop 1
	v_permlane16_swap_b32 v64, v65
	s_nop 1
	s_mov_b64 s[24:25], -1
	v_add_f32_e32 v64, v64, v65
	v_mov_b32_e32 v65, v64
	s_nop 1
	v_permlane32_swap_b32 v64, v65
	s_nop 1
	s_nop 0
	v_add_f32_e32 v64, v64, v65
	v_fmamk_f32 v64, v64, 0x3c800000, v251
	v_rsq_f32_e32 v64, v64
	v_mov_b32_e32 v65, 0x1fff
	v_bitop3_b32 v65, v80, s99, v65 bitop3:0x80
	v_cndmask_b32_e64 v82, 1.0, v64, s[42:43]
	v_and_b32_e32 v64, 0x1fff, v80
	v_lshrrev_b32_e32 v64, s58, v64
	v_or_b32_e32 v64, s26, v64
	v_mad_u32_u24 v64, v65, s59, v64
	v_ashrrev_i32_e32 v65, 31, v64
	v_lshl_add_u64 v[64:65], v[64:65], 0, s[4:5]
	v_lshlrev_b64 v[64:65], 7, v[64:65]
	v_lshl_add_u64 v[64:65], s[0:1], 0, v[64:65]
	v_lshl_add_u64 v[80:81], v[64:65], 0, v[114:115]
	v_pk_mul_f32 v[64:65], v[76:77], v[82:83] op_sel_hi:[1,0]
	v_pk_mul_f32 v[66:67], v[78:79], v[82:83] op_sel_hi:[1,0]
	v_pk_mul_f32 v[64:65], v[144:145], v[64:65]
	v_pk_mul_f32 v[66:67], v[146:147], v[66:67]
	v_pk_mul_f32 v[68:69], v[68:69], v[82:83] op_sel_hi:[1,0]
	v_pk_mul_f32 v[70:71], v[70:71], v[82:83] op_sel_hi:[1,0]
	v_pk_mul_f32 v[68:69], v[142:143], v[68:69]
	v_pk_mul_f32 v[70:71], v[148:149], v[70:71]
	v_cvt_pk_bf16_f32 v64, v64, v65
	v_cvt_pk_bf16_f32 v65, v66, v67
	v_cvt_pk_bf16_f32 v66, v68, v69
	v_pk_mul_f32 v[68:69], v[92:93], v[82:83] op_sel_hi:[1,0]
	v_cvt_pk_bf16_f32 v67, v70, v71
	global_store_dwordx4 v[80:81], v[64:67], off nt
	v_pk_mul_f32 v[70:71], v[90:91], v[82:83] op_sel_hi:[1,0]
	v_pk_mul_f32 v[68:69], v[150:151], v[68:69]
	v_pk_mul_f32 v[64:65], v[72:73], v[82:83] op_sel_hi:[1,0]
	v_pk_mul_f32 v[66:67], v[74:75], v[82:83] op_sel_hi:[1,0]
	v_pk_mul_f32 v[64:65], v[152:153], v[64:65]
	v_pk_mul_f32 v[66:67], v[154:155], v[66:67]
	v_cvt_pk_bf16_f32 v64, v64, v65
	v_pk_mul_f32 v[70:71], v[156:157], v[70:71]
	v_cvt_pk_bf16_f32 v65, v66, v67
	v_cvt_pk_bf16_f32 v66, v68, v69
	s_nop 0
	v_cvt_pk_bf16_f32 v67, v70, v71
	global_store_dwordx4 v[80:81], v[64:67], off offset:64 nt
	s_cbranch_vccnz .LBB0_192
	ds_read_b32 v66, v162 offset:512
	s_mov_b64 s[24:25], 0

;     __device__ __forceinline__ void operator()(const f32x4 (&acc)[2][2][4][2], const Unit& u, int wr, int wc, int fr, int fq, const LAS float* rt) const {
;     ...
;             for (int m = 0; m < 4; ++m) {
;                 const int row = row0 + ai * 128 + m * 16; const float rs = rt ? rt[wr * 64 + fr + ai * 128 + m * 16] : row_rstd(ssq, row);
;                 f32x4 v[2][2]; float ss = 0.f;
; #pragma unroll
;                 for (int bj = 0; bj < 2; ++bj)
; #pragma unroll
;                     for (int n = 0; n < 2; ++n) { v[bj][n] = acc[ai][bj][m][n] * rs; const f32x4 q = v[bj][n] * v[bj][n]; ss += (q[0] + q[1]) + (q[2] + q[3]); }
;                 ss = sum_x16_x32(ss);
;                 const float sc = kind < 2 ? __builtin_amdgcn_rsqf(ss * (1.f / 64.f) + RMS_EPS) : 1.f;
;                 const int tt = row & (SEQ - 1); const int prow = (row & ~(SEQ - 1)) + (tt & ((1 << rsh) - 1)) * (SEQ >> rsh) + (tt >> rsh);
; #pragma unroll
;                 for (int bj = 0; bj < 2; ++bj)
;                     gst<u32x4>((kind == 0 ? Oq : Okv + (size_t)(kind - 1) * 16 * M * 64) + ((size_t)(4 * (u.pn & 3) + wc) * M + prow) * 64 + 32 * bj + 8 * fq, pack8(v[bj][0] * sc * gv[bj][0], v[bj][1] * sc * gv[bj][1]));
.LBB0_194:
	s_waitcnt lgkmcnt(0)
	v_pk_mul_f32 v[62:63], v[62:63], v[66:67] op_sel_hi:[1,0]
	v_pk_mul_f32 v[60:61], v[60:61], v[66:67] op_sel_hi:[1,0]
	v_pk_mul_f32 v[68:69], v[62:63], v[62:63]
	v_pk_mul_f32 v[70:71], v[60:61], v[60:61]
	v_pk_mul_f32 v[54:55], v[54:55], v[66:67] op_sel_hi:[1,0]
	v_pk_mov_b32 v[72:73], v[70:71], v[68:69] op_sel:[1,0]
	v_mov_b32_e32 v71, v69
	v_pk_mul_f32 v[52:53], v[52:53], v[66:67] op_sel_hi:[1,0]
	v_pk_add_f32 v[68:69], v[72:73], v[70:71]
	v_pk_mul_f32 v[70:71], v[54:55], v[54:55]
	v_pk_mul_f32 v[72:73], v[52:53], v[52:53]
	v_pk_mul_f32 v[56:57], v[56:57], v[66:67] op_sel_hi:[1,0]
	v_pk_mov_b32 v[74:75], v[72:73], v[70:71] op_sel:[1,0]
	v_mov_b32_e32 v73, v71
	v_pk_add_f32 v[70:71], v[74:75], v[72:73]
	v_pk_mul_f32 v[74:75], v[56:57], v[56:57]
	v_pk_mul_f32 v[58:59], v[58:59], v[66:67] op_sel_hi:[1,0]
	v_add_f32_e32 v67, v74, v75
	v_pk_mul_f32 v[74:75], v[50:51], v[66:67] op_sel_hi:[1,0]
	v_pk_mul_f32 v[48:49], v[48:49], v[66:67] op_sel_hi:[1,0]
	v_pk_add_f32 v[68:69], v[68:69], v[68:69] op_sel_hi:[0,1]
	v_pk_add_f32 v[70:71], v[70:71], v[70:71] op_sel_hi:[0,1]
	v_pk_mul_f32 v[72:73], v[58:59], v[58:59]
	v_pk_mul_f32 v[50:51], v[74:75], v[74:75]
	v_pk_mul_f32 v[76:77], v[48:49], v[48:49]
	v_add_f32_e32 v73, v72, v73
	v_mov_b32_e32 v66, v76
	v_mov_b32_e32 v72, v77
	v_mov_b32_e32 v68, v50
	v_mov_b32_e32 v70, v51
	v_pk_add_f32 v[66:67], v[66:67], v[72:73]
	v_pk_add_f32 v[50:51], v[68:69], v[70:71]
	v_and_b32_e32 v65, 0x1fcf, v64
	v_pk_add_f32 v[50:51], v[66:67], v[50:51]
	v_lshrrev_b32_e32 v65, s58, v65
	v_add_f32_e32 v50, v50, v51
	v_mov_b32_e32 v51, v50
	s_nop 1
	v_permlane16_swap_b32 v50, v51
	s_nop 1
	v_bitop3_b32 v66, v64, s99, v252 bitop3:0x80
	v_add_f32_e32 v50, v50, v51
	v_mov_b32_e32 v51, v50
	s_nop 1
	v_permlane32_swap_b32 v50, v51
	s_nop 1
	v_mov_b32_e32 v115, v96
	v_add_f32_e32 v50, v50, v51
	v_fmamk_f32 v50, v50, 0x3c800000, v251
	v_rsq_f32_e32 v50, v50
	v_and_b32_e32 v51, 0xffffe000, v64
	v_or_b32_e32 v65, v65, v51
	v_mad_u32_u24 v66, v66, s59, v65
	v_ashrrev_i32_e32 v67, 31, v66
	v_cndmask_b32_e64 v50, 1.0, v50, s[42:43]
	v_lshl_add_u64 v[66:67], v[66:67], 0, s[4:5]
	v_lshlrev_b64 v[66:67], 7, v[66:67]
	v_pk_mul_f32 v[52:53], v[52:53], v[50:51] op_sel_hi:[1,0]
	v_pk_mul_f32 v[54:55], v[54:55], v[50:51] op_sel_hi:[1,0]
	v_lshl_add_u64 v[66:67], s[0:1], 0, v[66:67]
	v_pk_mul_f32 v[60:61], v[60:61], v[50:51] op_sel_hi:[1,0]
	v_pk_mul_f32 v[62:63], v[62:63], v[50:51] op_sel_hi:[1,0]
	v_pk_mul_f32 v[68:69], v[148:149], v[54:55]
	v_pk_mul_f32 v[54:55], v[142:143], v[52:53]
	v_lshl_add_u64 v[66:67], v[66:67], 0, v[114:115]
	v_pk_mul_f32 v[62:63], v[146:147], v[62:63]
	v_pk_mul_f32 v[60:61], v[144:145], v[60:61]
	v_pk_mul_f32 v[48:49], v[48:49], v[50:51] op_sel_hi:[1,0]
	v_cvt_pk_bf16_f32 v52, v60, v61
	v_cvt_pk_bf16_f32 v53, v62, v63
	v_cvt_pk_bf16_f32 v54, v54, v55
	v_cvt_pk_bf16_f32 v55, v68, v69
	global_store_dwordx4 v[66:67], v[52:55], off nt
	s_and_b64 vcc, exec, s[44:45]
	s_mov_b64 s[24:25], -1
	v_pk_mul_f32 v[52:53], v[56:57], v[50:51] op_sel_hi:[1,0]
	v_pk_mul_f32 v[54:55], v[58:59], v[50:51] op_sel_hi:[1,0]
	v_pk_mul_f32 v[52:53], v[152:153], v[52:53]
	v_pk_mul_f32 v[54:55], v[154:155], v[54:55]
	v_pk_mul_f32 v[56:57], v[74:75], v[50:51] op_sel_hi:[1,0]
	v_pk_mul_f32 v[48:49], v[150:151], v[48:49]
	v_pk_mul_f32 v[56:57], v[156:157], v[56:57]
	v_cvt_pk_bf16_f32 v52, v52, v53
	v_cvt_pk_bf16_f32 v53, v54, v55
	v_cvt_pk_bf16_f32 v54, v48, v49
	s_nop 0
	v_cvt_pk_bf16_f32 v55, v56, v57
	global_store_dwordx4 v[66:67], v[52:55], off offset:64 nt
	s_cbranch_vccnz .LBB0_196
	ds_read_b32 v50, v162 offset:576
	s_mov_b64 s[24:25], 0

;     __device__ __forceinline__ void operator()(const f32x4 (&acc)[2][2][4][2], const Unit& u, int wr, int wc, int fr, int fq, const LAS float* rt) const {
;     ...
;             for (int m = 0; m < 4; ++m) {
;                 const int row = row0 + ai * 128 + m * 16; const float rs = rt ? rt[wr * 64 + fr + ai * 128 + m * 16] : row_rstd(ssq, row);
;                 f32x4 v[2][2]; float ss = 0.f;
; #pragma unroll
;                 for (int bj = 0; bj < 2; ++bj)
; #pragma unroll
;                     for (int n = 0; n < 2; ++n) { v[bj][n] = acc[ai][bj][m][n] * rs; const f32x4 q = v[bj][n] * v[bj][n]; ss += (q[0] + q[1]) + (q[2] + q[3]); }
;                 ss = sum_x16_x32(ss);
;                 const float sc = kind < 2 ? __builtin_amdgcn_rsqf(ss * (1.f / 64.f) + RMS_EPS) : 1.f;
;                 const int tt = row & (SEQ - 1); const int prow = (row & ~(SEQ - 1)) + (tt & ((1 << rsh) - 1)) * (SEQ >> rsh) + (tt >> rsh);
; #pragma unroll
;                 for (int bj = 0; bj < 2; ++bj)
;                     gst<u32x4>((kind == 0 ? Oq : Okv + (size_t)(kind - 1) * 16 * M * 64) + ((size_t)(4 * (u.pn & 3) + wc) * M + prow) * 64 + 32 * bj + 8 * fq, pack8(v[bj][0] * sc * gv[bj][0], v[bj][1] * sc * gv[bj][1]));
.LBB0_198:
	s_waitcnt lgkmcnt(0)
	v_pk_mul_f32 v[46:47], v[46:47], v[50:51] op_sel_hi:[1,0]
	v_pk_mul_f32 v[44:45], v[44:45], v[50:51] op_sel_hi:[1,0]
	v_pk_mul_f32 v[52:53], v[46:47], v[46:47]
	v_pk_mul_f32 v[54:55], v[44:45], v[44:45]
	v_pk_mul_f32 v[38:39], v[38:39], v[50:51] op_sel_hi:[1,0]
	v_pk_mov_b32 v[56:57], v[54:55], v[52:53] op_sel:[1,0]
	v_mov_b32_e32 v55, v53
	v_pk_mul_f32 v[36:37], v[36:37], v[50:51] op_sel_hi:[1,0]
	v_pk_add_f32 v[52:53], v[56:57], v[54:55]
	v_pk_mul_f32 v[54:55], v[38:39], v[38:39]
	v_pk_mul_f32 v[56:57], v[36:37], v[36:37]
	v_pk_mul_f32 v[42:43], v[42:43], v[50:51] op_sel_hi:[1,0]
	v_pk_mov_b32 v[58:59], v[56:57], v[54:55] op_sel:[1,0]
	v_mov_b32_e32 v57, v55
	v_pk_add_f32 v[54:55], v[58:59], v[56:57]
	v_pk_mul_f32 v[40:41], v[40:41], v[50:51] op_sel_hi:[1,0]
	v_pk_mul_f32 v[60:61], v[34:35], v[50:51] op_sel_hi:[1,0]
	v_pk_mul_f32 v[62:63], v[32:33], v[50:51] op_sel_hi:[1,0]
	v_pk_add_f32 v[52:53], v[52:53], v[52:53] op_sel_hi:[0,1]
	v_pk_add_f32 v[54:55], v[54:55], v[54:55] op_sel_hi:[0,1]
	v_pk_mul_f32 v[56:57], v[42:43], v[42:43]
	v_pk_mul_f32 v[58:59], v[40:41], v[40:41]
	v_pk_mul_f32 v[32:33], v[60:61], v[60:61]
	v_pk_mul_f32 v[34:35], v[62:63], v[62:63]
	v_add_f32_e32 v59, v58, v59
	v_add_f32_e32 v57, v56, v57
	v_mov_b32_e32 v58, v34
	v_mov_b32_e32 v56, v35
	v_mov_b32_e32 v52, v32
	v_mov_b32_e32 v54, v33
	v_pk_add_f32 v[34:35], v[58:59], v[56:57]
	v_pk_add_f32 v[32:33], v[52:53], v[54:55]
	v_mov_b32_e32 v115, v96
	v_pk_add_f32 v[32:33], v[34:35], v[32:33]
	s_and_b64 vcc, exec, s[44:45]
	v_add_f32_e32 v32, v32, v33
	v_mov_b32_e32 v33, v32
	s_nop 1
	v_permlane16_swap_b32 v33, v32
	s_nop 1
	s_mov_b64 s[24:25], -1
	v_add_f32_e32 v32, v33, v32
	v_mov_b32_e32 v33, v32
	s_nop 1
	v_permlane32_swap_b32 v33, v32
	s_nop 1
	s_nop 0
	v_add_f32_e32 v32, v33, v32
	v_fmamk_f32 v32, v32, 0x3c800000, v251
	v_rsq_f32_e32 v32, v32
	v_mov_b32_e32 v33, 0x1fdf
	v_bitop3_b32 v33, v48, s99, v33 bitop3:0x80
	v_cndmask_b32_e64 v50, 1.0, v32, s[42:43]
	v_and_b32_e32 v32, 0x1fdf, v48
	v_lshrrev_b32_e32 v32, s58, v32
	v_or_b32_e32 v32, v32, v51
	v_mad_u32_u24 v32, v33, s59, v32
	v_ashrrev_i32_e32 v33, 31, v32
	v_lshl_add_u64 v[32:33], v[32:33], 0, s[4:5]
	v_lshlrev_b64 v[32:33], 7, v[32:33]
	v_lshl_add_u64 v[32:33], s[0:1], 0, v[32:33]
	v_lshl_add_u64 v[48:49], v[32:33], 0, v[114:115]
	v_pk_mul_f32 v[32:33], v[44:45], v[50:51] op_sel_hi:[1,0]
	v_pk_mul_f32 v[34:35], v[46:47], v[50:51] op_sel_hi:[1,0]
	v_pk_mul_f32 v[32:33], v[144:145], v[32:33]
	v_pk_mul_f32 v[34:35], v[146:147], v[34:35]
	v_pk_mul_f32 v[36:37], v[36:37], v[50:51] op_sel_hi:[1,0]
	v_pk_mul_f32 v[38:39], v[38:39], v[50:51] op_sel_hi:[1,0]
	v_pk_mul_f32 v[36:37], v[142:143], v[36:37]
	v_pk_mul_f32 v[38:39], v[148:149], v[38:39]
	v_cvt_pk_bf16_f32 v32, v32, v33
	v_cvt_pk_bf16_f32 v33, v34, v35
	v_cvt_pk_bf16_f32 v34, v36, v37
	v_pk_mul_f32 v[36:37], v[62:63], v[50:51] op_sel_hi:[1,0]
	v_cvt_pk_bf16_f32 v35, v38, v39
	global_store_dwordx4 v[48:49], v[32:35], off nt
	v_pk_mul_f32 v[38:39], v[60:61], v[50:51] op_sel_hi:[1,0]
	v_pk_mul_f32 v[36:37], v[150:151], v[36:37]
	v_pk_mul_f32 v[32:33], v[40:41], v[50:51] op_sel_hi:[1,0]
	v_pk_mul_f32 v[34:35], v[42:43], v[50:51] op_sel_hi:[1,0]
	v_pk_mul_f32 v[32:33], v[152:153], v[32:33]
	v_pk_mul_f32 v[34:35], v[154:155], v[34:35]
	v_cvt_pk_bf16_f32 v32, v32, v33
	v_pk_mul_f32 v[38:39], v[156:157], v[38:39]
	v_cvt_pk_bf16_f32 v33, v34, v35
	v_cvt_pk_bf16_f32 v34, v36, v37
	s_nop 0
	v_cvt_pk_bf16_f32 v35, v38, v39
	global_store_dwordx4 v[48:49], v[32:35], off offset:64 nt
	s_cbranch_vccnz .LBB0_200
	ds_read_b32 v34, v162 offset:640
	s_mov_b64 s[24:25], 0

;     __device__ __forceinline__ void operator()(const f32x4 (&acc)[2][2][4][2], const Unit& u, int wr, int wc, int fr, int fq, const LAS float* rt) const {
;     ...
;             for (int m = 0; m < 4; ++m) {
;                 const int row = row0 + ai * 128 + m * 16; const float rs = rt ? rt[wr * 64 + fr + ai * 128 + m * 16] : row_rstd(ssq, row);
;                 f32x4 v[2][2]; float ss = 0.f;
; #pragma unroll
;                 for (int bj = 0; bj < 2; ++bj)
; #pragma unroll
;                     for (int n = 0; n < 2; ++n) { v[bj][n] = acc[ai][bj][m][n] * rs; const f32x4 q = v[bj][n] * v[bj][n]; ss += (q[0] + q[1]) + (q[2] + q[3]); }
;                 ss = sum_x16_x32(ss);
;                 const float sc = kind < 2 ? __builtin_amdgcn_rsqf(ss * (1.f / 64.f) + RMS_EPS) : 1.f;
;                 const int tt = row & (SEQ - 1); const int prow = (row & ~(SEQ - 1)) + (tt & ((1 << rsh) - 1)) * (SEQ >> rsh) + (tt >> rsh);
; #pragma unroll
;                 for (int bj = 0; bj < 2; ++bj)
;                     gst<u32x4>((kind == 0 ? Oq : Okv + (size_t)(kind - 1) * 16 * M * 64) + ((size_t)(4 * (u.pn & 3) + wc) * M + prow) * 64 + 32 * bj + 8 * fq, pack8(v[bj][0] * sc * gv[bj][0], v[bj][1] * sc * gv[bj][1]));
.LBB0_202:
	s_waitcnt lgkmcnt(0)
	v_pk_mul_f32 v[30:31], v[30:31], v[34:35] op_sel_hi:[1,0]
	v_pk_mul_f32 v[28:29], v[28:29], v[34:35] op_sel_hi:[1,0]
	v_pk_mul_f32 v[36:37], v[30:31], v[30:31]
	v_pk_mul_f32 v[38:39], v[28:29], v[28:29]
	v_pk_mul_f32 v[22:23], v[22:23], v[34:35] op_sel_hi:[1,0]
	v_pk_mov_b32 v[40:41], v[38:39], v[36:37] op_sel:[1,0]
	v_mov_b32_e32 v39, v37
	v_pk_mul_f32 v[20:21], v[20:21], v[34:35] op_sel_hi:[1,0]
	v_pk_add_f32 v[36:37], v[40:41], v[38:39]
	v_pk_mul_f32 v[38:39], v[22:23], v[22:23]
	v_pk_mul_f32 v[40:41], v[20:21], v[20:21]
	v_pk_mul_f32 v[24:25], v[24:25], v[34:35] op_sel_hi:[1,0]
	v_pk_mov_b32 v[42:43], v[40:41], v[38:39] op_sel:[1,0]
	v_mov_b32_e32 v41, v39
	v_pk_add_f32 v[38:39], v[42:43], v[40:41]
	v_pk_mul_f32 v[42:43], v[24:25], v[24:25]
	v_pk_mul_f32 v[26:27], v[26:27], v[34:35] op_sel_hi:[1,0]
	v_add_f32_e32 v35, v42, v43
	v_pk_mul_f32 v[42:43], v[18:19], v[34:35] op_sel_hi:[1,0]
	v_pk_mul_f32 v[44:45], v[16:17], v[34:35] op_sel_hi:[1,0]
	v_pk_add_f32 v[36:37], v[36:37], v[36:37] op_sel_hi:[0,1]
	v_pk_add_f32 v[38:39], v[38:39], v[38:39] op_sel_hi:[0,1]
	v_pk_mul_f32 v[40:41], v[26:27], v[26:27]
	v_pk_mul_f32 v[16:17], v[42:43], v[42:43]
	v_pk_mul_f32 v[18:19], v[44:45], v[44:45]
	v_add_f32_e32 v41, v40, v41
	v_mov_b32_e32 v34, v18
	v_mov_b32_e32 v40, v19
	v_mov_b32_e32 v36, v16
	v_mov_b32_e32 v38, v17
	v_pk_add_f32 v[18:19], v[34:35], v[40:41]
	v_pk_add_f32 v[16:17], v[36:37], v[38:39]
	v_mov_b32_e32 v115, v96
	v_pk_add_f32 v[16:17], v[18:19], v[16:17]
	s_and_b64 vcc, exec, s[44:45]
	v_add_f32_e32 v16, v16, v17
	v_mov_b32_e32 v17, v16
	s_nop 1
	v_permlane16_swap_b32 v16, v17
	s_nop 1
	s_mov_b64 s[24:25], -1
	v_add_f32_e32 v16, v16, v17
	v_mov_b32_e32 v17, v16
	s_nop 1
	v_permlane32_swap_b32 v16, v17
	s_nop 1
	s_nop 0
	v_add_f32_e32 v16, v16, v17
	v_fmamk_f32 v16, v16, 0x3c800000, v251
	v_rsq_f32_e32 v16, v16
	v_mov_b32_e32 v17, 0x1fef
	v_bitop3_b32 v17, v32, s99, v17 bitop3:0x80
	v_cndmask_b32_e64 v34, 1.0, v16, s[42:43]
	v_and_b32_e32 v16, 0x1fef, v32
	v_lshrrev_b32_e32 v16, s58, v16
	v_or_b32_e32 v16, v16, v51
	v_mad_u32_u24 v16, v17, s59, v16
	v_ashrrev_i32_e32 v17, 31, v16
	v_lshl_add_u64 v[16:17], v[16:17], 0, s[4:5]
	v_lshlrev_b64 v[16:17], 7, v[16:17]
	v_lshl_add_u64 v[16:17], s[0:1], 0, v[16:17]
	v_lshl_add_u64 v[32:33], v[16:17], 0, v[114:115]
	v_pk_mul_f32 v[16:17], v[28:29], v[34:35] op_sel_hi:[1,0]
	v_pk_mul_f32 v[18:19], v[30:31], v[34:35] op_sel_hi:[1,0]
	v_pk_mul_f32 v[16:17], v[144:145], v[16:17]
	v_pk_mul_f32 v[18:19], v[146:147], v[18:19]
	v_pk_mul_f32 v[20:21], v[20:21], v[34:35] op_sel_hi:[1,0]
	v_pk_mul_f32 v[22:23], v[22:23], v[34:35] op_sel_hi:[1,0]
	v_pk_mul_f32 v[20:21], v[142:143], v[20:21]
	v_pk_mul_f32 v[22:23], v[148:149], v[22:23]
	v_cvt_pk_bf16_f32 v16, v16, v17
	v_cvt_pk_bf16_f32 v17, v18, v19
	v_cvt_pk_bf16_f32 v18, v20, v21
	v_pk_mul_f32 v[20:21], v[44:45], v[34:35] op_sel_hi:[1,0]
	v_cvt_pk_bf16_f32 v19, v22, v23
	global_store_dwordx4 v[32:33], v[16:19], off nt
	v_pk_mul_f32 v[22:23], v[42:43], v[34:35] op_sel_hi:[1,0]
	v_pk_mul_f32 v[20:21], v[150:151], v[20:21]
	v_pk_mul_f32 v[16:17], v[24:25], v[34:35] op_sel_hi:[1,0]
	v_pk_mul_f32 v[18:19], v[26:27], v[34:35] op_sel_hi:[1,0]
	v_pk_mul_f32 v[16:17], v[152:153], v[16:17]
	v_pk_mul_f32 v[18:19], v[154:155], v[18:19]
	v_cvt_pk_bf16_f32 v16, v16, v17
	v_pk_mul_f32 v[22:23], v[156:157], v[22:23]
	v_cvt_pk_bf16_f32 v17, v18, v19
	v_cvt_pk_bf16_f32 v18, v20, v21
	s_nop 0
	v_cvt_pk_bf16_f32 v19, v22, v23
	global_store_dwordx4 v[32:33], v[16:19], off offset:64 nt
	s_cbranch_vccnz .LBB0_204
	ds_read_b32 v18, v162 offset:704
	s_mov_b64 s[24:25], 0

; #define PG8_BAR __builtin_amdgcn_s_barrier()
; template <class Epi, class Sched, bool ALIGN_EPI = false, bool SP2 = false>
; __device__ __forceinline__ void gemm_phase(PG8_LAS unsigned char* lds, const Gemm g, const Sched& S, const Epi& E) {
;     ...
;         if (!has_next) break;
; #pragma unroll
;         for (int a = 0; a < 2; ++a)
; #pragma unroll
;             for (int b = 0; b < 2; ++b)
; #pragma unroll
;                 for (int m = 0; m < 4; ++m)
; #pragma unroll
;                     for (int n = 0; n < 2; ++n) acc[a][b][m][n] = (f32x4){0.f, 0.f, 0.f, 0.f};
;         cur = nxt; cA = nA; cB = nB; ++ui;
;         if constexpr (ALIGN_EPI) { if (wr == 1) PG8_BAR; }
;     __device__ __forceinline__ void operator()(const f32x4 (&acc)[2][2][4][2], const Unit& u, int wr, int wc, int fr, int fq, const LAS float* rt) const {
;     ...
;             for (int m = 0; m < 4; ++m) {
;                 const int row = row0 + ai * 128 + m * 16; const float rs = rt ? rt[wr * 64 + fr + ai * 128 + m * 16] : row_rstd(ssq, row);
;                 f32x4 v[2][2]; float ss = 0.f;
; #pragma unroll
;                 for (int bj = 0; bj < 2; ++bj)
; #pragma unroll
;                     for (int n = 0; n < 2; ++n) { v[bj][n] = acc[ai][bj][m][n] * rs; const f32x4 q = v[bj][n] * v[bj][n]; ss += (q[0] + q[1]) + (q[2] + q[3]); }
;                 ss = sum_x16_x32(ss);
;                 const float sc = kind < 2 ? __builtin_amdgcn_rsqf(ss * (1.f / 64.f) + RMS_EPS) : 1.f;
;                 const int tt = row & (SEQ - 1); const int prow = (row & ~(SEQ - 1)) + (tt & ((1 << rsh) - 1)) * (SEQ >> rsh) + (tt >> rsh);
; #pragma unroll
;                 for (int bj = 0; bj < 2; ++bj)
;                     gst<u32x4>((kind == 0 ? Oq : Okv + (size_t)(kind - 1) * 16 * M * 64) + ((size_t)(4 * (u.pn & 3) + wc) * M + prow) * 64 + 32 * bj + 8 * fq, pack8(v[bj][0] * sc * gv[bj][0], v[bj][1] * sc * gv[bj][1]));
.LBB0_206:
	s_waitcnt lgkmcnt(0)
	v_pk_mul_f32 v[14:15], v[14:15], v[18:19] op_sel_hi:[1,0]
	v_pk_mul_f32 v[12:13], v[12:13], v[18:19] op_sel_hi:[1,0]
	v_pk_mul_f32 v[20:21], v[14:15], v[14:15]
	v_pk_mul_f32 v[22:23], v[12:13], v[12:13]
	v_pk_mul_f32 v[6:7], v[6:7], v[18:19] op_sel_hi:[1,0]
	v_pk_mov_b32 v[24:25], v[22:23], v[20:21] op_sel:[1,0]
	v_mov_b32_e32 v23, v21
	v_pk_mul_f32 v[4:5], v[4:5], v[18:19] op_sel_hi:[1,0]
	v_pk_add_f32 v[20:21], v[24:25], v[22:23]
	v_pk_mul_f32 v[22:23], v[6:7], v[6:7]
	v_pk_mul_f32 v[24:25], v[4:5], v[4:5]
	v_pk_mul_f32 v[8:9], v[8:9], v[18:19] op_sel_hi:[1,0]
	v_pk_mov_b32 v[26:27], v[24:25], v[22:23] op_sel:[1,0]
	v_mov_b32_e32 v25, v23
	v_pk_add_f32 v[22:23], v[26:27], v[24:25]
	v_pk_mul_f32 v[26:27], v[8:9], v[8:9]
	v_pk_mul_f32 v[10:11], v[10:11], v[18:19] op_sel_hi:[1,0]
	v_add_f32_e32 v19, v26, v27
	v_pk_mul_f32 v[26:27], v[2:3], v[18:19] op_sel_hi:[1,0]
	v_pk_mul_f32 v[28:29], v[0:1], v[18:19] op_sel_hi:[1,0]
	v_pk_add_f32 v[20:21], v[20:21], v[20:21] op_sel_hi:[0,1]
	v_pk_add_f32 v[22:23], v[22:23], v[22:23] op_sel_hi:[0,1]
	v_pk_mul_f32 v[24:25], v[10:11], v[10:11]
	v_pk_mul_f32 v[0:1], v[26:27], v[26:27]
	v_pk_mul_f32 v[2:3], v[28:29], v[28:29]
	v_add_f32_e32 v25, v24, v25
	v_mov_b32_e32 v18, v2
	v_mov_b32_e32 v24, v3
	v_mov_b32_e32 v20, v0
	v_mov_b32_e32 v22, v1
	v_pk_add_f32 v[2:3], v[18:19], v[24:25]
	v_pk_add_f32 v[0:1], v[20:21], v[22:23]
	v_mov_b32_e32 v115, v96
	v_pk_add_f32 v[0:1], v[2:3], v[0:1]
	s_nop 0
	v_add_f32_e32 v0, v0, v1
	v_mov_b32_e32 v1, v0
	s_nop 1
	v_permlane16_swap_b32 v1, v0
	s_nop 1
	s_nop 0
	v_add_f32_e32 v0, v1, v0
	v_mov_b32_e32 v1, v0
	s_nop 1
	v_permlane32_swap_b32 v1, v0
	s_nop 1
	s_nop 0
	v_add_f32_e32 v0, v1, v0
	v_fmamk_f32 v0, v0, 0x3c800000, v251
	v_rsq_f32_e32 v0, v0
	v_mov_b32_e32 v1, 0x1fff
	v_bitop3_b32 v1, v16, s99, v1 bitop3:0x80
	v_cndmask_b32_e64 v18, 1.0, v0, s[42:43]
	v_and_b32_e32 v0, 0x1fff, v16
	v_lshrrev_b32_e32 v0, s58, v0
	v_or_b32_e32 v0, v0, v51
	v_mad_u32_u24 v0, v1, s59, v0
	v_ashrrev_i32_e32 v1, 31, v0
	v_lshl_add_u64 v[0:1], v[0:1], 0, s[4:5]
	v_lshlrev_b64 v[0:1], 7, v[0:1]
	v_lshl_add_u64 v[0:1], s[0:1], 0, v[0:1]
	v_lshl_add_u64 v[16:17], v[0:1], 0, v[114:115]
	v_pk_mul_f32 v[0:1], v[12:13], v[18:19] op_sel_hi:[1,0]
	v_pk_mul_f32 v[2:3], v[14:15], v[18:19] op_sel_hi:[1,0]
	v_pk_mul_f32 v[0:1], v[144:145], v[0:1]
	v_pk_mul_f32 v[2:3], v[146:147], v[2:3]
	v_pk_mul_f32 v[4:5], v[4:5], v[18:19] op_sel_hi:[1,0]
	v_pk_mul_f32 v[6:7], v[6:7], v[18:19] op_sel_hi:[1,0]
	v_pk_mul_f32 v[4:5], v[142:143], v[4:5]
	v_pk_mul_f32 v[6:7], v[148:149], v[6:7]
	v_cvt_pk_bf16_f32 v0, v0, v1
	v_cvt_pk_bf16_f32 v1, v2, v3
	v_cvt_pk_bf16_f32 v2, v4, v5
	v_readlane_b32 s0, v255, 33
	v_cvt_pk_bf16_f32 v3, v6, v7
	global_store_dwordx4 v[16:17], v[0:3], off nt
	v_readlane_b32 s1, v255, 34
	v_pk_mul_f32 v[4:5], v[28:29], v[18:19] op_sel_hi:[1,0]
	v_pk_mul_f32 v[0:1], v[8:9], v[18:19] op_sel_hi:[1,0]
	v_pk_mul_f32 v[2:3], v[10:11], v[18:19] op_sel_hi:[1,0]
	v_pk_mul_f32 v[0:1], v[152:153], v[0:1]
	v_pk_mul_f32 v[2:3], v[154:155], v[2:3]
	v_pk_mul_f32 v[6:7], v[26:27], v[18:19] op_sel_hi:[1,0]
	s_andn2_b64 vcc, exec, s[0:1]
	s_mov_b64 s[0:1], -1
	v_pk_mul_f32 v[6:7], v[156:157], v[6:7]
	v_pk_mul_f32 v[4:5], v[150:151], v[4:5]
	v_cvt_pk_bf16_f32 v0, v0, v1
	v_cvt_pk_bf16_f32 v1, v2, v3
	s_nop 0
	v_cvt_pk_bf16_f32 v2, v4, v5
	v_cvt_pk_bf16_f32 v3, v6, v7
	global_store_dwordx4 v[16:17], v[0:3], off offset:64 nt
	s_cbranch_vccnz .LBB0_157
	v_readlane_b32 s0, v255, 42
	v_readlane_b32 s1, v255, 43
	s_andn2_b64 vcc, exec, s[0:1]
	s_cbranch_vccnz .LBB0_156
	s_barrier
	s_branch .LBB0_156

;     __device__ __forceinline__ void operator()(const f32x4 (&acc)[2][2][4][2], const Unit& u, int wr, int wc, int fr, int fq) const {
;         const int row0 = u.pm * 256 + wr * 64 + fr, col0 = u.pn * 256 + wc * 32 + 8 * fq;
;         bf16_t* hbk = hb + (size_t)(u.pn * 4 + (wc >> 1)) * M * 64 + (wc & 1) * 32 + 8 * fq; constexpr size_t BJS = (size_t)2 * M * 64;
;         const bf16_t* hrow = hbk + (size_t)row0 * 64;
; #pragma unroll
;         for (int ai = 0; ai < 2; ++ai) {
;             u32x4 bq[4][2];
; #pragma unroll
;             for (int m = 0; m < 4; ++m)
; #pragma unroll
;                 for (int bj = 0; bj < 2; ++bj) bq[m][bj] = gld<u32x4>(hrow + bj * BJS + (size_t)(ai * 128 + m * 16) * 64);
;             asm volatile("" ::: "memory");
; #pragma unroll
;             for (int m = 0; m < 4; ++m) {
;                 const int row = row0 + ai * 128 + m * 16; const size_t off = (size_t)row * D + col0; float ss = 0.f;
; #pragma unroll
;                 for (int bj = 0; bj < 2; ++bj) {
;                     const u32x4 q = bq[m][bj];
;                     const f32x4 b0 = (f32x4){bflo(q.x), bfhi(q.x), bflo(q.y), bfhi(q.y)}, b1 = (f32x4){bflo(q.z), bfhi(q.z), bflo(q.w), bfhi(q.w)};
;                     const f32x4 h0 = b0 + acc[ai][bj][m][0] * scale, h1 = b1 + acc[ai][bj][m][1] * scale;
;                     if (out32) { gst<f32x4>(out32 + off + bj * 128, h0); gst<f32x4>(out32 + off + bj * 128 + 4, h1); }
.LBB0_350:
	s_lshl_b32 s2, s53, 8
	v_readlane_b32 s3, v255, 5
	v_mov_b32_e32 v122, v232
	s_add_i32 s2, s2, s3
	v_readlane_b32 s3, v255, 31
	v_and_or_b32 v174, v122, 15, s2
	s_lshl_b32 s2, s4, 8
	v_bfe_u32 v189, v122, 4, 2
	s_or_b32 s2, s2, s3
	v_lshl_or_b32 v172, v189, 3, s2
	s_lshl_b32 s24, s4, 2
	v_readlane_b32 s2, v255, 9
	s_or_b32 s2, s24, s2
	s_ashr_i32 s3, s2, 31
	s_lshl_b64 s[2:3], s[2:3], 22
	s_add_u32 s2, s11, s2
	s_addc_u32 s3, s9, s3
	v_lshlrev_b32_e32 v122, 4, v189
	v_mov_b32_e32 v123, v96
	v_ashrrev_i32_e32 v175, 31, v174
	v_lshl_add_u64 v[122:123], s[2:3], 0, v[122:123]
	v_lshlrev_b64 v[124:125], 7, v[174:175]
	v_lshl_add_u64 v[170:171], v[122:123], 0, v[124:125]
	s_mov_b32 s2, 0x800000
	v_add_co_u32_e32 v122, vcc, s2, v170
	s_mov_b32 s2, 0x801000
	s_nop 0
	v_addc_co_u32_e32 v123, vcc, 0, v171, vcc
	v_add_co_u32_e32 v124, vcc, s2, v170
	s_movk_i32 s2, 0x1000
	s_nop 0
	v_addc_co_u32_e32 v125, vcc, 0, v171, vcc
	global_load_dwordx4 v[180:183], v[170:171], off
	global_load_dwordx4 v[154:157], v[124:125], off offset:-4096
	global_load_dwordx4 v[150:153], v[170:171], off offset:2048
	global_load_dwordx4 v[146:149], v[122:123], off offset:2048
	v_add_co_u32_e32 v122, vcc, s2, v170
	v_ashrrev_i32_e32 v173, 31, v172
	s_nop 0
	v_addc_co_u32_e32 v123, vcc, 0, v171, vcc
	global_load_dwordx4 v[142:145], v[122:123], off
	global_load_dwordx4 v[138:141], v[124:125], off
	global_load_dwordx4 v[126:129], v[122:123], off offset:2048
	s_nop 0
	global_load_dwordx4 v[122:125], v[124:125], off offset:2048
	v_lshlrev_b64 v[176:177], 10, v[174:175]
	v_lshl_add_u64 v[176:177], v[176:177], 0, v[172:173]
	s_mov_b64 s[44:45], -1
	s_andn2_b64 vcc, exec, s[16:17]
	v_lshl_add_u64 v[176:177], v[176:177], 2, s[60:61]
	s_waitcnt vmcnt(0)
	v_lshlrev_b32_e32 v178, 16, v180
	v_and_b32_e32 v179, 0xffff0000, v180
	v_lshlrev_b32_e32 v180, 16, v181
	v_and_b32_e32 v181, 0xffff0000, v181
	v_lshlrev_b32_e32 v184, 16, v182
	v_and_b32_e32 v185, 0xffff0000, v182
	v_lshlrev_b32_e32 v182, 16, v183
	v_and_b32_e32 v183, 0xffff0000, v183
	v_pk_fma_f32 v[134:135], s[30:31], v[134:135], v[178:179]
	v_cndmask_b32_e64 v178, 0, 1, s[16:17]
	v_pk_fma_f32 v[136:137], s[50:51], v[136:137], v[180:181]
	v_pk_fma_f32 v[132:133], s[50:51], v[132:133], v[182:183]
	v_pk_fma_f32 v[130:131], s[30:31], v[130:131], v[184:185]
	v_cmp_ne_u32_e64 s[42:43], 1, v178
	s_cbranch_vccnz .LBB0_352
	s_mov_b64 s[44:45], 0
	global_store_dwordx4 v[176:177], v[134:137], off nt
	global_store_dwordx4 v[176:177], v[130:133], off offset:16 nt

;     __device__ __forceinline__ void operator()(const f32x4 (&acc)[2][2][4][2], const Unit& u, int wr, int wc, int fr, int fq) const {
;     ...
;             for (int m = 0; m < 4; ++m) {
;                 const int row = row0 + ai * 128 + m * 16; const size_t off = (size_t)row * D + col0; float ss = 0.f;
; #pragma unroll
;                 for (int bj = 0; bj < 2; ++bj) {
;                     const u32x4 q = bq[m][bj];
;                     const f32x4 b0 = (f32x4){bflo(q.x), bfhi(q.x), bflo(q.y), bfhi(q.y)}, b1 = (f32x4){bflo(q.z), bfhi(q.z), bflo(q.w), bfhi(q.w)};
;                     const f32x4 h0 = b0 + acc[ai][bj][m][0] * scale, h1 = b1 + acc[ai][bj][m][1] * scale;
;                     if (out32) { gst<f32x4>(out32 + off + bj * 128, h0); gst<f32x4>(out32 + off + bj * 128 + 4, h1); }
.LBB0_354:
	v_lshlrev_b32_e32 v130, 16, v154
	v_and_b32_e32 v131, 0xffff0000, v154
	v_lshlrev_b32_e32 v132, 16, v155
	v_and_b32_e32 v133, 0xffff0000, v155
	v_lshlrev_b32_e32 v134, 16, v156
	v_and_b32_e32 v135, 0xffff0000, v156
	v_lshlrev_b32_e32 v136, 16, v157
	v_and_b32_e32 v137, 0xffff0000, v157
	v_pk_fma_f32 v[120:121], s[50:51], v[120:121], v[132:133]
	v_pk_fma_f32 v[118:119], s[30:31], v[118:119], v[130:131]
	v_pk_fma_f32 v[116:117], s[50:51], v[116:117], v[136:137]
	v_pk_fma_f32 v[114:115], s[30:31], v[114:115], v[134:135]
	s_and_b64 vcc, exec, s[42:43]
	s_mov_b64 s[44:45], -1
	s_cbranch_vccnz .LBB0_356
	s_mov_b64 s[44:45], 0
	global_store_dwordx4 v[176:177], v[118:121], off offset:512 nt
	global_store_dwordx4 v[176:177], v[114:117], off offset:528 nt

;     __device__ __forceinline__ void operator()(const f32x4 (&acc)[2][2][4][2], const Unit& u, int wr, int wc, int fr, int fq) const {
;     ...
;             for (int m = 0; m < 4; ++m) {
;                 const int row = row0 + ai * 128 + m * 16; const size_t off = (size_t)row * D + col0; float ss = 0.f;
; #pragma unroll
;                 for (int bj = 0; bj < 2; ++bj) {
;                     const u32x4 q = bq[m][bj];
;                     const f32x4 b0 = (f32x4){bflo(q.x), bfhi(q.x), bflo(q.y), bfhi(q.y)}, b1 = (f32x4){bflo(q.z), bfhi(q.z), bflo(q.w), bfhi(q.w)};
;                     const f32x4 h0 = b0 + acc[ai][bj][m][0] * scale, h1 = b1 + acc[ai][bj][m][1] * scale;
;                     if (out32) { gst<f32x4>(out32 + off + bj * 128, h0); gst<f32x4>(out32 + off + bj * 128 + 4, h1); }
.LBB0_362:
	v_or_b32_e32 v114, 16, v174
	v_ashrrev_i32_e32 v115, 31, v114
	v_lshlrev_b64 v[116:117], 10, v[114:115]
	v_lshl_add_u64 v[116:117], v[116:117], 0, v[172:173]
	v_lshlrev_b32_e32 v118, 16, v150
	v_and_b32_e32 v119, 0xffff0000, v150
	v_lshlrev_b32_e32 v120, 16, v151
	v_and_b32_e32 v121, 0xffff0000, v151
	v_lshlrev_b32_e32 v130, 16, v152
	v_and_b32_e32 v131, 0xffff0000, v152
	v_lshlrev_b32_e32 v132, 16, v153
	v_and_b32_e32 v133, 0xffff0000, v153
	v_pk_fma_f32 v[112:113], s[50:51], v[112:113], v[120:121]
	v_pk_fma_f32 v[110:111], s[30:31], v[110:111], v[118:119]
	v_pk_fma_f32 v[108:109], s[50:51], v[108:109], v[132:133]
	v_pk_fma_f32 v[106:107], s[30:31], v[106:107], v[130:131]
	s_mov_b64 s[58:59], -1
	s_and_b64 vcc, exec, s[42:43]
	v_lshl_add_u64 v[116:117], v[116:117], 2, s[60:61]
	s_cbranch_vccnz .LBB0_364
	s_mov_b64 s[58:59], 0
	global_store_dwordx4 v[116:117], v[110:113], off nt
	global_store_dwordx4 v[116:117], v[106:109], off offset:16 nt

;     __device__ __forceinline__ void operator()(const f32x4 (&acc)[2][2][4][2], const Unit& u, int wr, int wc, int fr, int fq) const {
;     ...
;             for (int m = 0; m < 4; ++m) {
;                 const int row = row0 + ai * 128 + m * 16; const size_t off = (size_t)row * D + col0; float ss = 0.f;
; #pragma unroll
;                 for (int bj = 0; bj < 2; ++bj) {
;                     const u32x4 q = bq[m][bj];
;                     const f32x4 b0 = (f32x4){bflo(q.x), bfhi(q.x), bflo(q.y), bfhi(q.y)}, b1 = (f32x4){bflo(q.z), bfhi(q.z), bflo(q.w), bfhi(q.w)};
;                     const f32x4 h0 = b0 + acc[ai][bj][m][0] * scale, h1 = b1 + acc[ai][bj][m][1] * scale;
;                     if (out32) { gst<f32x4>(out32 + off + bj * 128, h0); gst<f32x4>(out32 + off + bj * 128 + 4, h1); }
.LBB0_366:
	v_lshlrev_b32_e32 v106, 16, v146
	v_and_b32_e32 v107, 0xffff0000, v146
	v_lshlrev_b32_e32 v108, 16, v147
	v_and_b32_e32 v109, 0xffff0000, v147
	v_lshlrev_b32_e32 v110, 16, v148
	v_and_b32_e32 v111, 0xffff0000, v148
	v_lshlrev_b32_e32 v112, 16, v149
	v_and_b32_e32 v113, 0xffff0000, v149
	v_pk_fma_f32 v[104:105], s[50:51], v[104:105], v[108:109]
	v_pk_fma_f32 v[102:103], s[30:31], v[102:103], v[106:107]
	v_pk_fma_f32 v[100:101], s[50:51], v[100:101], v[112:113]
	v_pk_fma_f32 v[98:99], s[30:31], v[98:99], v[110:111]
	s_and_b64 vcc, exec, s[42:43]
	s_mov_b64 s[58:59], -1
	s_cbranch_vccnz .LBB0_369
	global_store_dwordx4 v[116:117], v[102:105], off offset:512 nt
	global_store_dwordx4 v[116:117], v[98:101], off offset:528 nt
	s_cbranch_execz .LBB0_370

;     __device__ __forceinline__ void operator()(const f32x4 (&acc)[2][2][4][2], const Unit& u, int wr, int wc, int fr, int fq) const {
;     ...
;             for (int m = 0; m < 4; ++m) {
;                 const int row = row0 + ai * 128 + m * 16; const size_t off = (size_t)row * D + col0; float ss = 0.f;
; #pragma unroll
;                 for (int bj = 0; bj < 2; ++bj) {
;                     const u32x4 q = bq[m][bj];
;                     const f32x4 b0 = (f32x4){bflo(q.x), bfhi(q.x), bflo(q.y), bfhi(q.y)}, b1 = (f32x4){bflo(q.z), bfhi(q.z), bflo(q.w), bfhi(q.w)};
;                     const f32x4 h0 = b0 + acc[ai][bj][m][0] * scale, h1 = b1 + acc[ai][bj][m][1] * scale;
;                     if (out32) { gst<f32x4>(out32 + off + bj * 128, h0); gst<f32x4>(out32 + off + bj * 128 + 4, h1); }
.LBB0_374:
	v_or_b32_e32 v98, 32, v174
	v_ashrrev_i32_e32 v99, 31, v98
	v_lshlrev_b64 v[100:101], 10, v[98:99]
	v_lshl_add_u64 v[100:101], v[100:101], 0, v[172:173]
	v_lshlrev_b32_e32 v102, 16, v142
	v_and_b32_e32 v103, 0xffff0000, v142
	v_lshlrev_b32_e32 v104, 16, v143
	v_and_b32_e32 v105, 0xffff0000, v143
	v_lshlrev_b32_e32 v106, 16, v144
	v_and_b32_e32 v107, 0xffff0000, v144
	v_lshlrev_b32_e32 v108, 16, v145
	v_and_b32_e32 v109, 0xffff0000, v145
	v_pk_fma_f32 v[94:95], s[50:51], v[94:95], v[104:105]
	v_pk_fma_f32 v[92:93], s[30:31], v[92:93], v[102:103]
	v_pk_fma_f32 v[90:91], s[50:51], v[90:91], v[108:109]
	v_pk_fma_f32 v[88:89], s[30:31], v[88:89], v[106:107]
	s_mov_b64 s[58:59], -1
	s_and_b64 vcc, exec, s[42:43]
	v_lshl_add_u64 v[100:101], v[100:101], 2, s[60:61]
	s_cbranch_vccnz .LBB0_376
	s_mov_b64 s[58:59], 0
	global_store_dwordx4 v[100:101], v[92:95], off nt
	global_store_dwordx4 v[100:101], v[88:91], off offset:16 nt

;     __device__ __forceinline__ void operator()(const f32x4 (&acc)[2][2][4][2], const Unit& u, int wr, int wc, int fr, int fq) const {
;     ...
;             for (int m = 0; m < 4; ++m) {
;                 const int row = row0 + ai * 128 + m * 16; const size_t off = (size_t)row * D + col0; float ss = 0.f;
; #pragma unroll
;                 for (int bj = 0; bj < 2; ++bj) {
;                     const u32x4 q = bq[m][bj];
;                     const f32x4 b0 = (f32x4){bflo(q.x), bfhi(q.x), bflo(q.y), bfhi(q.y)}, b1 = (f32x4){bflo(q.z), bfhi(q.z), bflo(q.w), bfhi(q.w)};
;                     const f32x4 h0 = b0 + acc[ai][bj][m][0] * scale, h1 = b1 + acc[ai][bj][m][1] * scale;
;                     if (out32) { gst<f32x4>(out32 + off + bj * 128, h0); gst<f32x4>(out32 + off + bj * 128 + 4, h1); }
.LBB0_378:
	v_lshlrev_b32_e32 v88, 16, v138
	v_and_b32_e32 v89, 0xffff0000, v138
	v_lshlrev_b32_e32 v90, 16, v139
	v_and_b32_e32 v91, 0xffff0000, v139
	v_lshlrev_b32_e32 v92, 16, v140
	v_and_b32_e32 v93, 0xffff0000, v140
	v_lshlrev_b32_e32 v94, 16, v141
	v_and_b32_e32 v95, 0xffff0000, v141
	v_pk_fma_f32 v[86:87], s[50:51], v[86:87], v[90:91]
	v_pk_fma_f32 v[84:85], s[30:31], v[84:85], v[88:89]
	v_pk_fma_f32 v[82:83], s[50:51], v[82:83], v[94:95]
	v_pk_fma_f32 v[80:81], s[30:31], v[80:81], v[92:93]
	s_and_b64 vcc, exec, s[42:43]
	s_mov_b64 s[58:59], -1
	s_cbranch_vccnz .LBB0_381
	global_store_dwordx4 v[100:101], v[84:87], off offset:512 nt
	global_store_dwordx4 v[100:101], v[80:83], off offset:528 nt
	s_cbranch_execz .LBB0_382

;     __device__ __forceinline__ void operator()(const f32x4 (&acc)[2][2][4][2], const Unit& u, int wr, int wc, int fr, int fq) const {
;     ...
;             for (int m = 0; m < 4; ++m) {
;                 const int row = row0 + ai * 128 + m * 16; const size_t off = (size_t)row * D + col0; float ss = 0.f;
; #pragma unroll
;                 for (int bj = 0; bj < 2; ++bj) {
;                     const u32x4 q = bq[m][bj];
;                     const f32x4 b0 = (f32x4){bflo(q.x), bfhi(q.x), bflo(q.y), bfhi(q.y)}, b1 = (f32x4){bflo(q.z), bfhi(q.z), bflo(q.w), bfhi(q.w)};
;                     const f32x4 h0 = b0 + acc[ai][bj][m][0] * scale, h1 = b1 + acc[ai][bj][m][1] * scale;
;                     if (out32) { gst<f32x4>(out32 + off + bj * 128, h0); gst<f32x4>(out32 + off + bj * 128 + 4, h1); }
.LBB0_386:
	v_or_b32_e32 v80, 48, v174
	v_ashrrev_i32_e32 v81, 31, v80
	v_lshlrev_b64 v[82:83], 10, v[80:81]
	v_lshl_add_u64 v[82:83], v[82:83], 0, v[172:173]
	v_lshlrev_b32_e32 v84, 16, v126
	v_and_b32_e32 v85, 0xffff0000, v126
	v_lshlrev_b32_e32 v86, 16, v127
	v_and_b32_e32 v87, 0xffff0000, v127
	v_lshlrev_b32_e32 v88, 16, v128
	v_and_b32_e32 v89, 0xffff0000, v128
	v_lshlrev_b32_e32 v90, 16, v129
	v_and_b32_e32 v91, 0xffff0000, v129
	v_pk_fma_f32 v[78:79], s[50:51], v[78:79], v[86:87]
	v_pk_fma_f32 v[76:77], s[30:31], v[76:77], v[84:85]
	v_pk_fma_f32 v[74:75], s[50:51], v[74:75], v[90:91]
	v_pk_fma_f32 v[72:73], s[30:31], v[72:73], v[88:89]
	s_mov_b64 s[58:59], -1
	s_and_b64 vcc, exec, s[42:43]
	v_lshl_add_u64 v[82:83], v[82:83], 2, s[60:61]
	s_cbranch_vccnz .LBB0_388
	s_mov_b64 s[58:59], 0
	global_store_dwordx4 v[82:83], v[76:79], off nt
	global_store_dwordx4 v[82:83], v[72:75], off offset:16 nt

;     __device__ __forceinline__ void operator()(const f32x4 (&acc)[2][2][4][2], const Unit& u, int wr, int wc, int fr, int fq) const {
;     ...
;             for (int m = 0; m < 4; ++m) {
;                 const int row = row0 + ai * 128 + m * 16; const size_t off = (size_t)row * D + col0; float ss = 0.f;
; #pragma unroll
;                 for (int bj = 0; bj < 2; ++bj) {
;                     const u32x4 q = bq[m][bj];
;                     const f32x4 b0 = (f32x4){bflo(q.x), bfhi(q.x), bflo(q.y), bfhi(q.y)}, b1 = (f32x4){bflo(q.z), bfhi(q.z), bflo(q.w), bfhi(q.w)};
;                     const f32x4 h0 = b0 + acc[ai][bj][m][0] * scale, h1 = b1 + acc[ai][bj][m][1] * scale;
;                     if (out32) { gst<f32x4>(out32 + off + bj * 128, h0); gst<f32x4>(out32 + off + bj * 128 + 4, h1); }
.LBB0_390:
	v_lshlrev_b32_e32 v72, 16, v122
	v_and_b32_e32 v73, 0xffff0000, v122
	v_lshlrev_b32_e32 v74, 16, v123
	v_and_b32_e32 v75, 0xffff0000, v123
	v_lshlrev_b32_e32 v76, 16, v124
	v_and_b32_e32 v77, 0xffff0000, v124
	v_lshlrev_b32_e32 v78, 16, v125
	v_and_b32_e32 v79, 0xffff0000, v125
	v_pk_fma_f32 v[70:71], s[50:51], v[70:71], v[74:75]
	v_pk_fma_f32 v[68:69], s[30:31], v[68:69], v[72:73]
	v_pk_fma_f32 v[66:67], s[50:51], v[66:67], v[78:79]
	v_pk_fma_f32 v[64:65], s[30:31], v[64:65], v[76:77]
	s_and_b64 vcc, exec, s[42:43]
	s_mov_b64 s[58:59], -1
	s_cbranch_vccnz .LBB0_393
	global_store_dwordx4 v[82:83], v[68:71], off offset:512 nt
	global_store_dwordx4 v[82:83], v[64:67], off offset:528 nt
	s_cbranch_execz .LBB0_394

;     __device__ __forceinline__ void operator()(const f32x4 (&acc)[2][2][4][2], const Unit& u, int wr, int wc, int fr, int fq) const {
;     ...
;         for (int ai = 0; ai < 2; ++ai) {
;             u32x4 bq[4][2];
; #pragma unroll
;             for (int m = 0; m < 4; ++m)
; #pragma unroll
;                 for (int bj = 0; bj < 2; ++bj) bq[m][bj] = gld<u32x4>(hrow + bj * BJS + (size_t)(ai * 128 + m * 16) * 64);
;             asm volatile("" ::: "memory");
; #pragma unroll
;             for (int m = 0; m < 4; ++m) {
;                 const int row = row0 + ai * 128 + m * 16; const size_t off = (size_t)row * D + col0; float ss = 0.f;
; #pragma unroll
;                 for (int bj = 0; bj < 2; ++bj) {
;                     const u32x4 q = bq[m][bj];
;                     const f32x4 b0 = (f32x4){bflo(q.x), bfhi(q.x), bflo(q.y), bfhi(q.y)}, b1 = (f32x4){bflo(q.z), bfhi(q.z), bflo(q.w), bfhi(q.w)};
;                     const f32x4 h0 = b0 + acc[ai][bj][m][0] * scale, h1 = b1 + acc[ai][bj][m][1] * scale;
;                     if (out32) { gst<f32x4>(out32 + off + bj * 128, h0); gst<f32x4>(out32 + off + bj * 128 + 4, h1); }
.LBB0_398:
	v_add_co_u32_e32 v64, vcc, 0x4000, v170
	v_add_u32_e32 v92, 0x80, v174
	s_nop 0
	v_addc_co_u32_e32 v65, vcc, 0, v171, vcc
	v_add_co_u32_e32 v66, vcc, 0x804000, v170
	v_ashrrev_i32_e32 v93, 31, v92
	s_nop 0
	v_addc_co_u32_e32 v67, vcc, 0, v171, vcc
	global_load_dwordx4 v[98:101], v[64:65], off
	global_load_dwordx4 v[84:87], v[64:65], off offset:2048
	global_load_dwordx4 v[88:91], v[66:67], off
	global_load_dwordx4 v[80:83], v[66:67], off offset:2048
	v_add_co_u32_e32 v64, vcc, 0x5000, v170
	v_lshlrev_b64 v[94:95], 10, v[92:93]
	s_nop 0
	v_addc_co_u32_e32 v65, vcc, 0, v171, vcc
	v_add_co_u32_e32 v66, vcc, 0x805000, v170
	v_lshl_add_u64 v[94:95], v[94:95], 0, v[172:173]
	s_nop 0
	v_addc_co_u32_e32 v67, vcc, 0, v171, vcc
	global_load_dwordx4 v[76:79], v[64:65], off
	global_load_dwordx4 v[68:71], v[64:65], off offset:2048
	global_load_dwordx4 v[72:75], v[66:67], off
	s_nop 0
	global_load_dwordx4 v[64:67], v[66:67], off offset:2048
	s_mov_b64 s[58:59], -1
	s_and_b64 vcc, exec, s[42:43]
	v_lshl_add_u64 v[94:95], v[94:95], 2, s[60:61]
	s_waitcnt vmcnt(7)
	v_lshlrev_b32_e32 v102, 16, v98
	v_and_b32_e32 v103, 0xffff0000, v98
	v_lshlrev_b32_e32 v98, 16, v99
	v_and_b32_e32 v99, 0xffff0000, v99
	v_lshlrev_b32_e32 v104, 16, v100
	v_and_b32_e32 v105, 0xffff0000, v100
	v_lshlrev_b32_e32 v100, 16, v101
	v_and_b32_e32 v101, 0xffff0000, v101
	v_pk_fma_f32 v[62:63], s[50:51], v[62:63], v[98:99]
	v_pk_fma_f32 v[60:61], s[30:31], v[60:61], v[102:103]
	v_pk_fma_f32 v[58:59], s[50:51], v[58:59], v[100:101]
	v_pk_fma_f32 v[56:57], s[30:31], v[56:57], v[104:105]
	s_cbranch_vccnz .LBB0_400
	s_mov_b64 s[58:59], 0
	global_store_dwordx4 v[94:95], v[60:63], off nt
	global_store_dwordx4 v[94:95], v[56:59], off offset:16 nt

;     __device__ __forceinline__ void operator()(const f32x4 (&acc)[2][2][4][2], const Unit& u, int wr, int wc, int fr, int fq) const {
;     ...
;             for (int m = 0; m < 4; ++m) {
;                 const int row = row0 + ai * 128 + m * 16; const size_t off = (size_t)row * D + col0; float ss = 0.f;
; #pragma unroll
;                 for (int bj = 0; bj < 2; ++bj) {
;                     const u32x4 q = bq[m][bj];
;                     const f32x4 b0 = (f32x4){bflo(q.x), bfhi(q.x), bflo(q.y), bfhi(q.y)}, b1 = (f32x4){bflo(q.z), bfhi(q.z), bflo(q.w), bfhi(q.w)};
;                     const f32x4 h0 = b0 + acc[ai][bj][m][0] * scale, h1 = b1 + acc[ai][bj][m][1] * scale;
;                     if (out32) { gst<f32x4>(out32 + off + bj * 128, h0); gst<f32x4>(out32 + off + bj * 128 + 4, h1); }
.LBB0_402:
	s_waitcnt vmcnt(5)
	v_lshlrev_b32_e32 v56, 16, v88
	v_and_b32_e32 v57, 0xffff0000, v88
	v_lshlrev_b32_e32 v58, 16, v89
	v_and_b32_e32 v59, 0xffff0000, v89
	v_lshlrev_b32_e32 v60, 16, v90
	v_and_b32_e32 v61, 0xffff0000, v90
	v_lshlrev_b32_e32 v62, 16, v91
	v_and_b32_e32 v63, 0xffff0000, v91
	v_pk_fma_f32 v[54:55], s[50:51], v[54:55], v[58:59]
	v_pk_fma_f32 v[52:53], s[30:31], v[52:53], v[56:57]
	v_pk_fma_f32 v[50:51], s[50:51], v[50:51], v[62:63]
	v_pk_fma_f32 v[48:49], s[30:31], v[48:49], v[60:61]
	s_and_b64 vcc, exec, s[42:43]
	s_mov_b64 s[58:59], -1
	s_cbranch_vccnz .LBB0_405
	global_store_dwordx4 v[94:95], v[52:55], off offset:512 nt
	global_store_dwordx4 v[94:95], v[48:51], off offset:528 nt
	s_cbranch_execz .LBB0_406

;     __device__ __forceinline__ void operator()(const f32x4 (&acc)[2][2][4][2], const Unit& u, int wr, int wc, int fr, int fq) const {
;     ...
;             for (int m = 0; m < 4; ++m) {
;                 const int row = row0 + ai * 128 + m * 16; const size_t off = (size_t)row * D + col0; float ss = 0.f;
; #pragma unroll
;                 for (int bj = 0; bj < 2; ++bj) {
;                     const u32x4 q = bq[m][bj];
;                     const f32x4 b0 = (f32x4){bflo(q.x), bfhi(q.x), bflo(q.y), bfhi(q.y)}, b1 = (f32x4){bflo(q.z), bfhi(q.z), bflo(q.w), bfhi(q.w)};
;                     const f32x4 h0 = b0 + acc[ai][bj][m][0] * scale, h1 = b1 + acc[ai][bj][m][1] * scale;
;                     if (out32) { gst<f32x4>(out32 + off + bj * 128, h0); gst<f32x4>(out32 + off + bj * 128 + 4, h1); }
.LBB0_410:
	v_add_u32_e32 v48, 0x90, v174
	v_ashrrev_i32_e32 v49, 31, v48
	v_lshlrev_b64 v[50:51], 10, v[48:49]
	v_lshl_add_u64 v[50:51], v[50:51], 0, v[172:173]
	v_lshlrev_b32_e32 v52, 16, v84
	v_and_b32_e32 v53, 0xffff0000, v84
	v_lshlrev_b32_e32 v54, 16, v85
	v_and_b32_e32 v55, 0xffff0000, v85
	v_lshlrev_b32_e32 v56, 16, v86
	v_and_b32_e32 v57, 0xffff0000, v86
	v_lshlrev_b32_e32 v58, 16, v87
	v_and_b32_e32 v59, 0xffff0000, v87
	v_pk_fma_f32 v[46:47], s[50:51], v[46:47], v[54:55]
	v_pk_fma_f32 v[44:45], s[30:31], v[44:45], v[52:53]
	v_pk_fma_f32 v[42:43], s[50:51], v[42:43], v[58:59]
	v_pk_fma_f32 v[40:41], s[30:31], v[40:41], v[56:57]
	s_mov_b64 s[58:59], -1
	s_and_b64 vcc, exec, s[42:43]
	v_lshl_add_u64 v[50:51], v[50:51], 2, s[60:61]
	s_cbranch_vccnz .LBB0_412
	s_mov_b64 s[58:59], 0
	global_store_dwordx4 v[50:51], v[44:47], off nt
	global_store_dwordx4 v[50:51], v[40:43], off offset:16 nt

;     __device__ __forceinline__ void operator()(const f32x4 (&acc)[2][2][4][2], const Unit& u, int wr, int wc, int fr, int fq) const {
;     ...
;             for (int m = 0; m < 4; ++m) {
;                 const int row = row0 + ai * 128 + m * 16; const size_t off = (size_t)row * D + col0; float ss = 0.f;
; #pragma unroll
;                 for (int bj = 0; bj < 2; ++bj) {
;                     const u32x4 q = bq[m][bj];
;                     const f32x4 b0 = (f32x4){bflo(q.x), bfhi(q.x), bflo(q.y), bfhi(q.y)}, b1 = (f32x4){bflo(q.z), bfhi(q.z), bflo(q.w), bfhi(q.w)};
;                     const f32x4 h0 = b0 + acc[ai][bj][m][0] * scale, h1 = b1 + acc[ai][bj][m][1] * scale;
;                     if (out32) { gst<f32x4>(out32 + off + bj * 128, h0); gst<f32x4>(out32 + off + bj * 128 + 4, h1); }
.LBB0_414:
	s_waitcnt vmcnt(4)
	v_lshlrev_b32_e32 v40, 16, v80
	v_and_b32_e32 v41, 0xffff0000, v80
	v_lshlrev_b32_e32 v42, 16, v81
	v_and_b32_e32 v43, 0xffff0000, v81
	v_lshlrev_b32_e32 v44, 16, v82
	v_and_b32_e32 v45, 0xffff0000, v82
	v_lshlrev_b32_e32 v46, 16, v83
	v_and_b32_e32 v47, 0xffff0000, v83
	v_pk_fma_f32 v[38:39], s[50:51], v[38:39], v[42:43]
	v_pk_fma_f32 v[36:37], s[30:31], v[36:37], v[40:41]
	v_pk_fma_f32 v[34:35], s[50:51], v[34:35], v[46:47]
	v_pk_fma_f32 v[32:33], s[30:31], v[32:33], v[44:45]
	s_and_b64 vcc, exec, s[42:43]
	s_mov_b64 s[58:59], -1
	s_cbranch_vccnz .LBB0_417
	global_store_dwordx4 v[50:51], v[36:39], off offset:512 nt
	global_store_dwordx4 v[50:51], v[32:35], off offset:528 nt
	s_cbranch_execz .LBB0_418

;     __device__ __forceinline__ void operator()(const f32x4 (&acc)[2][2][4][2], const Unit& u, int wr, int wc, int fr, int fq) const {
;     ...
;             for (int m = 0; m < 4; ++m) {
;                 const int row = row0 + ai * 128 + m * 16; const size_t off = (size_t)row * D + col0; float ss = 0.f;
; #pragma unroll
;                 for (int bj = 0; bj < 2; ++bj) {
;                     const u32x4 q = bq[m][bj];
;                     const f32x4 b0 = (f32x4){bflo(q.x), bfhi(q.x), bflo(q.y), bfhi(q.y)}, b1 = (f32x4){bflo(q.z), bfhi(q.z), bflo(q.w), bfhi(q.w)};
;                     const f32x4 h0 = b0 + acc[ai][bj][m][0] * scale, h1 = b1 + acc[ai][bj][m][1] * scale;
;                     if (out32) { gst<f32x4>(out32 + off + bj * 128, h0); gst<f32x4>(out32 + off + bj * 128 + 4, h1); }
.LBB0_422:
	v_add_u32_e32 v32, 0xa0, v174
	v_ashrrev_i32_e32 v33, 31, v32
	v_lshlrev_b64 v[34:35], 10, v[32:33]
	v_lshl_add_u64 v[34:35], v[34:35], 0, v[172:173]
	s_waitcnt vmcnt(3)
	v_lshlrev_b32_e32 v36, 16, v76
	v_and_b32_e32 v37, 0xffff0000, v76
	v_lshlrev_b32_e32 v38, 16, v77
	v_and_b32_e32 v39, 0xffff0000, v77
	v_lshlrev_b32_e32 v40, 16, v78
	v_and_b32_e32 v41, 0xffff0000, v78
	v_lshlrev_b32_e32 v42, 16, v79
	v_and_b32_e32 v43, 0xffff0000, v79
	v_pk_fma_f32 v[30:31], s[50:51], v[30:31], v[38:39]
	v_pk_fma_f32 v[28:29], s[30:31], v[28:29], v[36:37]
	v_pk_fma_f32 v[26:27], s[50:51], v[26:27], v[42:43]
	v_pk_fma_f32 v[24:25], s[30:31], v[24:25], v[40:41]
	s_mov_b64 s[58:59], -1
	s_and_b64 vcc, exec, s[42:43]
	v_lshl_add_u64 v[34:35], v[34:35], 2, s[60:61]
	s_cbranch_vccnz .LBB0_424
	s_mov_b64 s[58:59], 0
	global_store_dwordx4 v[34:35], v[28:31], off nt
	global_store_dwordx4 v[34:35], v[24:27], off offset:16 nt

;     __device__ __forceinline__ void operator()(const f32x4 (&acc)[2][2][4][2], const Unit& u, int wr, int wc, int fr, int fq) const {
;     ...
;             for (int m = 0; m < 4; ++m) {
;                 const int row = row0 + ai * 128 + m * 16; const size_t off = (size_t)row * D + col0; float ss = 0.f;
; #pragma unroll
;                 for (int bj = 0; bj < 2; ++bj) {
;                     const u32x4 q = bq[m][bj];
;                     const f32x4 b0 = (f32x4){bflo(q.x), bfhi(q.x), bflo(q.y), bfhi(q.y)}, b1 = (f32x4){bflo(q.z), bfhi(q.z), bflo(q.w), bfhi(q.w)};
;                     const f32x4 h0 = b0 + acc[ai][bj][m][0] * scale, h1 = b1 + acc[ai][bj][m][1] * scale;
;                     if (out32) { gst<f32x4>(out32 + off + bj * 128, h0); gst<f32x4>(out32 + off + bj * 128 + 4, h1); }
.LBB0_426:
	s_waitcnt vmcnt(1)
	v_lshlrev_b32_e32 v24, 16, v72
	v_and_b32_e32 v25, 0xffff0000, v72
	v_lshlrev_b32_e32 v26, 16, v73
	v_and_b32_e32 v27, 0xffff0000, v73
	v_lshlrev_b32_e32 v28, 16, v74
	v_and_b32_e32 v29, 0xffff0000, v74
	v_lshlrev_b32_e32 v30, 16, v75
	v_and_b32_e32 v31, 0xffff0000, v75
	v_pk_fma_f32 v[22:23], s[50:51], v[22:23], v[26:27]
	v_pk_fma_f32 v[20:21], s[30:31], v[20:21], v[24:25]
	v_pk_fma_f32 v[18:19], s[50:51], v[18:19], v[30:31]
	v_pk_fma_f32 v[16:17], s[30:31], v[16:17], v[28:29]
	s_and_b64 vcc, exec, s[42:43]
	s_mov_b64 s[58:59], -1
	s_cbranch_vccnz .LBB0_429
	global_store_dwordx4 v[34:35], v[20:23], off offset:512 nt
	global_store_dwordx4 v[34:35], v[16:19], off offset:528 nt
	s_cbranch_execz .LBB0_430

;     __device__ __forceinline__ void operator()(const f32x4 (&acc)[2][2][4][2], const Unit& u, int wr, int wc, int fr, int fq) const {
;     ...
;             for (int m = 0; m < 4; ++m) {
;                 const int row = row0 + ai * 128 + m * 16; const size_t off = (size_t)row * D + col0; float ss = 0.f;
; #pragma unroll
;                 for (int bj = 0; bj < 2; ++bj) {
;                     const u32x4 q = bq[m][bj];
;                     const f32x4 b0 = (f32x4){bflo(q.x), bfhi(q.x), bflo(q.y), bfhi(q.y)}, b1 = (f32x4){bflo(q.z), bfhi(q.z), bflo(q.w), bfhi(q.w)};
;                     const f32x4 h0 = b0 + acc[ai][bj][m][0] * scale, h1 = b1 + acc[ai][bj][m][1] * scale;
;                     if (out32) { gst<f32x4>(out32 + off + bj * 128, h0); gst<f32x4>(out32 + off + bj * 128 + 4, h1); }
.LBB0_434:
	v_add_u32_e32 v16, 0xb0, v174
	v_ashrrev_i32_e32 v17, 31, v16
	v_lshlrev_b64 v[18:19], 10, v[16:17]
	v_lshl_add_u64 v[18:19], v[18:19], 0, v[172:173]
	v_lshlrev_b32_e32 v20, 16, v68
	v_and_b32_e32 v21, 0xffff0000, v68
	v_lshlrev_b32_e32 v22, 16, v69
	v_and_b32_e32 v23, 0xffff0000, v69
	v_lshlrev_b32_e32 v24, 16, v70
	v_and_b32_e32 v25, 0xffff0000, v70
	v_lshlrev_b32_e32 v26, 16, v71
	v_and_b32_e32 v27, 0xffff0000, v71
	v_pk_fma_f32 v[14:15], s[50:51], v[14:15], v[22:23]
	v_pk_fma_f32 v[12:13], s[30:31], v[12:13], v[20:21]
	v_pk_fma_f32 v[10:11], s[50:51], v[10:11], v[26:27]
	v_pk_fma_f32 v[8:9], s[30:31], v[8:9], v[24:25]
	s_mov_b64 s[58:59], -1
	s_and_b64 vcc, exec, s[42:43]
	v_lshl_add_u64 v[18:19], v[18:19], 2, s[60:61]
	s_cbranch_vccnz .LBB0_436
	s_mov_b64 s[58:59], 0
	global_store_dwordx4 v[18:19], v[12:15], off nt
	global_store_dwordx4 v[18:19], v[8:11], off offset:16 nt

;     __device__ __forceinline__ void operator()(const f32x4 (&acc)[2][2][4][2], const Unit& u, int wr, int wc, int fr, int fq) const {
;     ...
;             for (int m = 0; m < 4; ++m) {
;                 const int row = row0 + ai * 128 + m * 16; const size_t off = (size_t)row * D + col0; float ss = 0.f;
; #pragma unroll
;                 for (int bj = 0; bj < 2; ++bj) {
;                     const u32x4 q = bq[m][bj];
;                     const f32x4 b0 = (f32x4){bflo(q.x), bfhi(q.x), bflo(q.y), bfhi(q.y)}, b1 = (f32x4){bflo(q.z), bfhi(q.z), bflo(q.w), bfhi(q.w)};
;                     const f32x4 h0 = b0 + acc[ai][bj][m][0] * scale, h1 = b1 + acc[ai][bj][m][1] * scale;
;                     if (out32) { gst<f32x4>(out32 + off + bj * 128, h0); gst<f32x4>(out32 + off + bj * 128 + 4, h1); }
.LBB0_438:
	s_waitcnt vmcnt(0)
	v_lshlrev_b32_e32 v8, 16, v64
	v_and_b32_e32 v9, 0xffff0000, v64
	v_lshlrev_b32_e32 v10, 16, v65
	v_and_b32_e32 v11, 0xffff0000, v65
	v_lshlrev_b32_e32 v12, 16, v66
	v_and_b32_e32 v13, 0xffff0000, v66
	v_lshlrev_b32_e32 v14, 16, v67
	v_and_b32_e32 v15, 0xffff0000, v67
	v_pk_fma_f32 v[6:7], s[50:51], v[6:7], v[10:11]
	v_pk_fma_f32 v[4:5], s[30:31], v[4:5], v[8:9]
	v_pk_fma_f32 v[2:3], s[50:51], v[2:3], v[14:15]
	v_pk_fma_f32 v[0:1], s[30:31], v[0:1], v[12:13]
	s_and_b64 vcc, exec, s[42:43]
	s_mov_b64 s[42:43], -1
	s_cbranch_vccnz .LBB0_441
	global_store_dwordx4 v[18:19], v[4:7], off offset:512 nt
	global_store_dwordx4 v[18:19], v[0:3], off offset:528 nt
	s_cbranch_execz .LBB0_442

;     __device__ __forceinline__ void operator()(const f32x4 (&acc)[2][2][4][2], const Unit& u, int wr, int wc, int fr, int fq, const LAS float* rt) const {
;     ...
;         for (int ai = 0; ai < 2; ++ai)
; #pragma unroll
;             for (int m = 0; m < 4; ++m) {
;                 const int row = row0 + ai * 128 + m * 16; const float rs = rsv[ai][m], nrs = -rs * LOG2E, irs2 = __builtin_amdgcn_rcpf(rs * rs);
;                 f32x4 o[2];
; #pragma unroll
;                 for (int n = 0; n < 2; ++n) {
;                     const f32x4 g = acc[ai][0][m][n], up = acc[ai][1][m][n];
; #pragma unroll
;                     for (int e = 0; e < 4; e += 2) {
;                         typedef float f32x2 __attribute__((ext_vector_type(2)));
;                         const f32x2 gg = (f32x2){g[e], g[e + 1]}, uu = (f32x2){up[e], up[e + 1]};
;                         const f32x2 t = gg * nrs;
;                         f32x2 ex; ex.x = __builtin_amdgcn_exp2f(t.x); ex.y = __builtin_amdgcn_exp2f(t.y);
;                         const f32x2 d = ex * irs2 + irs2;
;                         f32x2 r; r.x = __builtin_amdgcn_rcpf(d.x); r.y = __builtin_amdgcn_rcpf(d.y);
;                         const f32x2 oo = (gg * uu) * r; o[n][e] = oo.x; o[n][e + 1] = oo.y; }
;                 }
;                 gst<u32x4>(Ob + (size_t)row * 64, pack8(o[0], o[1]));
.LBB0_515:
	s_waitcnt lgkmcnt(0)
	v_mul_f32_e32 v166, 0xbfb8aa3b, v164
	v_mul_f32_e32 v164, v164, v164
	v_pk_mul_f32 v[168:169], v[122:123], v[166:167] op_sel_hi:[1,0]
	v_pk_mul_f32 v[122:123], v[122:123], v[126:127]
	v_pk_mul_f32 v[126:127], v[114:115], v[166:167] op_sel_hi:[1,0]
	v_rcp_f32_e32 v164, v164
	v_exp_f32_e32 v126, v126
	v_exp_f32_e32 v127, v127
	v_pk_mul_f32 v[114:115], v[114:115], v[118:119]
	v_pk_mul_f32 v[128:129], v[124:125], v[128:129]
	v_pk_mul_f32 v[124:125], v[124:125], v[166:167] op_sel_hi:[1,0]
	v_pk_fma_f32 v[126:127], v[164:165], v[126:127], v[164:165] op_sel_hi:[0,1,0]
	v_rcp_f32_e32 v126, v126
	v_rcp_f32_e32 v127, v127
	v_exp_f32_e32 v168, v168
	v_exp_f32_e32 v169, v169
	v_exp_f32_e32 v124, v124
	v_pk_mul_f32 v[118:119], v[114:115], v[126:127]
	v_pk_mul_f32 v[114:115], v[116:117], v[166:167] op_sel_hi:[1,0]
	v_exp_f32_e32 v125, v125
	v_exp_f32_e32 v114, v114
	v_exp_f32_e32 v115, v115
	s_lshl_b32 s0, s55, 1
	s_or_b32 s0, s0, s51
	s_ashr_i32 s1, s0, 31
	v_pk_fma_f32 v[114:115], v[164:165], v[114:115], v[164:165] op_sel_hi:[0,1,0]
	v_pk_fma_f32 v[168:169], v[164:165], v[168:169], v[164:165] op_sel_hi:[0,1,0]
	v_pk_fma_f32 v[124:125], v[164:165], v[124:125], v[164:165] op_sel_hi:[0,1,0]
	v_rcp_f32_e32 v114, v114
	v_rcp_f32_e32 v115, v115
	s_lshl_b64 s[0:1], s[0:1], 22
	v_rcp_f32_e32 v168, v168
	v_rcp_f32_e32 v169, v169
	v_rcp_f32_e32 v124, v124
	v_rcp_f32_e32 v125, v125
	s_add_u32 s0, s52, s0
	s_addc_u32 s1, s53, s1
	v_and_b32_e32 v144, 48, v144
	v_mov_b32_e32 v145, v96
	v_pk_mul_f32 v[120:121], v[116:117], v[120:121]
	v_lshl_add_u64 v[144:145], s[0:1], 0, v[144:145]
	v_pk_mul_f32 v[120:121], v[120:121], v[114:115]
	v_lshlrev_b64 v[114:115], 7, v[154:155]
	v_pk_mul_f32 v[122:123], v[122:123], v[168:169]
	v_pk_mul_f32 v[124:125], v[128:129], v[124:125]
	v_lshl_add_u64 v[114:115], v[144:145], 0, v[114:115]
	v_cvt_pk_bf16_f32 v116, v122, v123
	v_cvt_pk_bf16_f32 v117, v124, v125
	v_cvt_pk_bf16_f32 v118, v118, v119
	v_cvt_pk_bf16_f32 v119, v120, v121
	global_store_dwordx4 v[114:115], v[116:119], off nt
	v_pk_mul_f32 v[112:113], v[108:109], v[112:113]
	v_pk_mul_f32 v[104:105], v[100:101], v[104:105]
	v_mul_f32_e32 v116, 0xbfb8aa3b, v163
	v_mul_f32_e32 v117, v163, v163
	v_pk_mul_f32 v[120:121], v[106:107], v[116:117] op_sel_hi:[1,0]
	v_pk_mul_f32 v[106:107], v[106:107], v[110:111]
	v_pk_mul_f32 v[110:111], v[98:99], v[116:117] op_sel_hi:[1,0]
	v_rcp_f32_e32 v118, v117
	v_exp_f32_e32 v110, v110
	v_exp_f32_e32 v111, v111
	v_pk_mul_f32 v[98:99], v[98:99], v[102:103]
	v_pk_mul_f32 v[108:109], v[108:109], v[116:117] op_sel_hi:[1,0]
	v_exp_f32_e32 v120, v120
	v_pk_fma_f32 v[110:111], v[118:119], v[110:111], v[118:119] op_sel_hi:[0,1,0]
	v_rcp_f32_e32 v110, v110
	v_rcp_f32_e32 v111, v111
	v_exp_f32_e32 v121, v121
	v_exp_f32_e32 v108, v108
	v_exp_f32_e32 v109, v109
	v_pk_mul_f32 v[102:103], v[98:99], v[110:111]
	v_pk_mul_f32 v[98:99], v[100:101], v[116:117] op_sel_hi:[1,0]
	v_pk_fma_f32 v[120:121], v[118:119], v[120:121], v[118:119] op_sel_hi:[0,1,0]
	v_exp_f32_e32 v98, v98
	v_exp_f32_e32 v99, v99
	v_pk_fma_f32 v[108:109], v[118:119], v[108:109], v[118:119] op_sel_hi:[0,1,0]
	v_rcp_f32_e32 v120, v120
	v_rcp_f32_e32 v121, v121
	v_pk_fma_f32 v[98:99], v[118:119], v[98:99], v[118:119] op_sel_hi:[0,1,0]
	v_rcp_f32_e32 v98, v98
	v_rcp_f32_e32 v99, v99
	v_rcp_f32_e32 v108, v108
	v_rcp_f32_e32 v109, v109
	v_pk_mul_f32 v[106:107], v[106:107], v[120:121]
	v_pk_mul_f32 v[104:105], v[104:105], v[98:99]
	v_lshlrev_b64 v[98:99], 7, v[152:153]
	v_pk_mul_f32 v[108:109], v[112:113], v[108:109]
	v_lshl_add_u64 v[110:111], v[144:145], 0, v[98:99]
	v_cvt_pk_bf16_f32 v98, v106, v107
	v_cvt_pk_bf16_f32 v99, v108, v109
	v_cvt_pk_bf16_f32 v100, v102, v103
	v_cvt_pk_bf16_f32 v101, v104, v105
	global_store_dwordx4 v[110:111], v[98:101], off nt
	v_pk_mul_f32 v[94:95], v[90:91], v[94:95]
	v_pk_mul_f32 v[86:87], v[82:83], v[86:87]
	v_mul_f32_e32 v98, 0xbfb8aa3b, v162
	v_mul_f32_e32 v99, v162, v162
	v_pk_mul_f32 v[102:103], v[88:89], v[98:99] op_sel_hi:[1,0]
	v_pk_mul_f32 v[88:89], v[88:89], v[92:93]
	v_pk_mul_f32 v[92:93], v[80:81], v[98:99] op_sel_hi:[1,0]
	v_rcp_f32_e32 v100, v99
	v_exp_f32_e32 v92, v92
	v_exp_f32_e32 v93, v93
	v_pk_mul_f32 v[80:81], v[80:81], v[84:85]
	v_pk_mul_f32 v[90:91], v[90:91], v[98:99] op_sel_hi:[1,0]
	v_exp_f32_e32 v102, v102
	v_pk_fma_f32 v[92:93], v[100:101], v[92:93], v[100:101] op_sel_hi:[0,1,0]
	v_rcp_f32_e32 v92, v92
	v_rcp_f32_e32 v93, v93
	v_exp_f32_e32 v103, v103
	v_exp_f32_e32 v90, v90
	v_exp_f32_e32 v91, v91
	v_pk_mul_f32 v[84:85], v[80:81], v[92:93]
	v_pk_mul_f32 v[80:81], v[82:83], v[98:99] op_sel_hi:[1,0]
	v_pk_fma_f32 v[102:103], v[100:101], v[102:103], v[100:101] op_sel_hi:[0,1,0]
	v_exp_f32_e32 v80, v80
	v_exp_f32_e32 v81, v81
	v_pk_fma_f32 v[90:91], v[100:101], v[90:91], v[100:101] op_sel_hi:[0,1,0]
	v_rcp_f32_e32 v102, v102
	v_rcp_f32_e32 v103, v103
	v_pk_fma_f32 v[80:81], v[100:101], v[80:81], v[100:101] op_sel_hi:[0,1,0]
	v_rcp_f32_e32 v80, v80
	v_rcp_f32_e32 v81, v81
	v_rcp_f32_e32 v90, v90
	v_rcp_f32_e32 v91, v91
	v_pk_mul_f32 v[88:89], v[88:89], v[102:103]
	v_pk_mul_f32 v[86:87], v[86:87], v[80:81]
	v_lshlrev_b64 v[80:81], 7, v[150:151]
	v_pk_mul_f32 v[90:91], v[94:95], v[90:91]
	v_lshl_add_u64 v[92:93], v[144:145], 0, v[80:81]
	v_cvt_pk_bf16_f32 v80, v88, v89
	v_cvt_pk_bf16_f32 v81, v90, v91
	v_cvt_pk_bf16_f32 v82, v84, v85
	v_cvt_pk_bf16_f32 v83, v86, v87
	global_store_dwordx4 v[92:93], v[80:83], off nt
	v_pk_mul_f32 v[78:79], v[74:75], v[78:79]
	v_pk_mul_f32 v[70:71], v[62:63], v[70:71]
	v_mul_f32_e32 v80, 0xbfb8aa3b, v161
	v_mul_f32_e32 v81, v161, v161
	v_pk_mul_f32 v[84:85], v[72:73], v[80:81] op_sel_hi:[1,0]
;     __device__ __forceinline__ void operator()(const f32x4 (&acc)[2][2][4][2], const Unit& u, int wr, int wc, int fr, int fq, const LAS float* rt) const {
;     ...
;         for (int ai = 0; ai < 2; ++ai)
; #pragma unroll
;             for (int m = 0; m < 4; ++m) {
;                 const int row = row0 + ai * 128 + m * 16; const float rs = rsv[ai][m], nrs = -rs * LOG2E, irs2 = __builtin_amdgcn_rcpf(rs * rs);
;                 f32x4 o[2];
; #pragma unroll
;                 for (int n = 0; n < 2; ++n) {
;                     const f32x4 g = acc[ai][0][m][n], up = acc[ai][1][m][n];
; #pragma unroll
;                     for (int e = 0; e < 4; e += 2) {
;                         typedef float f32x2 __attribute__((ext_vector_type(2)));
;                         const f32x2 gg = (f32x2){g[e], g[e + 1]}, uu = (f32x2){up[e], up[e + 1]};
;                         const f32x2 t = gg * nrs;
;                         f32x2 ex; ex.x = __builtin_amdgcn_exp2f(t.x); ex.y = __builtin_amdgcn_exp2f(t.y);
;                         const f32x2 d = ex * irs2 + irs2;
;                         f32x2 r; r.x = __builtin_amdgcn_rcpf(d.x); r.y = __builtin_amdgcn_rcpf(d.y);
;                         const f32x2 oo = (gg * uu) * r; o[n][e] = oo.x; o[n][e + 1] = oo.y; }
;                 }
;                 gst<u32x4>(Ob + (size_t)row * 64, pack8(o[0], o[1]));
	v_pk_mul_f32 v[72:73], v[72:73], v[76:77]
	v_pk_mul_f32 v[76:77], v[60:61], v[80:81] op_sel_hi:[1,0]
	v_rcp_f32_e32 v82, v81
	v_exp_f32_e32 v76, v76
	v_exp_f32_e32 v77, v77
	v_pk_mul_f32 v[60:61], v[60:61], v[68:69]
	v_pk_mul_f32 v[74:75], v[74:75], v[80:81] op_sel_hi:[1,0]
	v_exp_f32_e32 v84, v84
	v_pk_fma_f32 v[76:77], v[82:83], v[76:77], v[82:83] op_sel_hi:[0,1,0]
	v_rcp_f32_e32 v76, v76
	v_rcp_f32_e32 v77, v77
	v_exp_f32_e32 v85, v85
	v_exp_f32_e32 v74, v74
	v_exp_f32_e32 v75, v75
	v_pk_mul_f32 v[68:69], v[60:61], v[76:77]
	v_pk_mul_f32 v[60:61], v[62:63], v[80:81] op_sel_hi:[1,0]
	v_pk_fma_f32 v[84:85], v[82:83], v[84:85], v[82:83] op_sel_hi:[0,1,0]
	v_exp_f32_e32 v60, v60
	v_exp_f32_e32 v61, v61
	v_pk_fma_f32 v[74:75], v[82:83], v[74:75], v[82:83] op_sel_hi:[0,1,0]
	v_rcp_f32_e32 v84, v84
	v_rcp_f32_e32 v85, v85
	v_pk_fma_f32 v[60:61], v[82:83], v[60:61], v[82:83] op_sel_hi:[0,1,0]
	v_rcp_f32_e32 v60, v60
	v_rcp_f32_e32 v61, v61
	v_rcp_f32_e32 v74, v74
	v_rcp_f32_e32 v75, v75
	v_pk_mul_f32 v[72:73], v[72:73], v[84:85]
	v_pk_mul_f32 v[70:71], v[70:71], v[60:61]
	v_lshlrev_b64 v[60:61], 7, v[148:149]
	v_pk_mul_f32 v[74:75], v[78:79], v[74:75]
	v_lshl_add_u64 v[76:77], v[144:145], 0, v[60:61]
	v_cvt_pk_bf16_f32 v60, v72, v73
	v_cvt_pk_bf16_f32 v61, v74, v75
	v_cvt_pk_bf16_f32 v62, v68, v69
	v_cvt_pk_bf16_f32 v63, v70, v71
	global_store_dwordx4 v[76:77], v[60:63], off nt
	v_pk_mul_f32 v[66:67], v[58:59], v[66:67]
	v_pk_mul_f32 v[54:55], v[50:51], v[54:55]
	v_mul_f32_e32 v60, 0xbfb8aa3b, v160
	v_mul_f32_e32 v61, v160, v160
	v_pk_mul_f32 v[68:69], v[56:57], v[60:61] op_sel_hi:[1,0]
	v_pk_mul_f32 v[56:57], v[56:57], v[64:65]
	v_pk_mul_f32 v[64:65], v[48:49], v[60:61] op_sel_hi:[1,0]
	v_rcp_f32_e32 v62, v61
	v_exp_f32_e32 v64, v64
	v_exp_f32_e32 v65, v65
	v_pk_mul_f32 v[48:49], v[48:49], v[52:53]
	v_pk_mul_f32 v[58:59], v[58:59], v[60:61] op_sel_hi:[1,0]
	v_exp_f32_e32 v68, v68
	v_pk_fma_f32 v[64:65], v[62:63], v[64:65], v[62:63] op_sel_hi:[0,1,0]
	v_rcp_f32_e32 v64, v64
	v_rcp_f32_e32 v65, v65
	v_exp_f32_e32 v69, v69
	v_exp_f32_e32 v58, v58
	v_exp_f32_e32 v59, v59
	v_pk_mul_f32 v[52:53], v[48:49], v[64:65]
	v_pk_mul_f32 v[48:49], v[50:51], v[60:61] op_sel_hi:[1,0]
	v_pk_fma_f32 v[68:69], v[62:63], v[68:69], v[62:63] op_sel_hi:[0,1,0]
	v_exp_f32_e32 v48, v48
	v_exp_f32_e32 v49, v49
	v_pk_fma_f32 v[58:59], v[62:63], v[58:59], v[62:63] op_sel_hi:[0,1,0]
	v_rcp_f32_e32 v68, v68
	v_rcp_f32_e32 v69, v69
	v_pk_fma_f32 v[48:49], v[62:63], v[48:49], v[62:63] op_sel_hi:[0,1,0]
	v_rcp_f32_e32 v48, v48
	v_rcp_f32_e32 v49, v49
	v_rcp_f32_e32 v58, v58
	v_rcp_f32_e32 v59, v59
	v_pk_mul_f32 v[56:57], v[56:57], v[68:69]
	v_pk_mul_f32 v[54:55], v[54:55], v[48:49]
	v_lshlrev_b64 v[48:49], 7, v[146:147]
	v_pk_mul_f32 v[58:59], v[66:67], v[58:59]
	v_lshl_add_u64 v[60:61], v[144:145], 0, v[48:49]
	v_cvt_pk_bf16_f32 v48, v56, v57
	v_cvt_pk_bf16_f32 v49, v58, v59
	v_cvt_pk_bf16_f32 v50, v52, v53
	v_cvt_pk_bf16_f32 v51, v54, v55
	global_store_dwordx4 v[60:61], v[48:51], off nt
	v_pk_mul_f32 v[46:47], v[42:43], v[46:47]
	v_pk_mul_f32 v[38:39], v[34:35], v[38:39]
	v_mul_f32_e32 v48, 0xbfb8aa3b, v159
	v_mul_f32_e32 v49, v159, v159
	v_pk_mul_f32 v[52:53], v[40:41], v[48:49] op_sel_hi:[1,0]
	v_pk_mul_f32 v[40:41], v[40:41], v[44:45]
	v_pk_mul_f32 v[44:45], v[32:33], v[48:49] op_sel_hi:[1,0]
	v_rcp_f32_e32 v50, v49
	v_exp_f32_e32 v44, v44
	v_exp_f32_e32 v45, v45
	v_pk_mul_f32 v[32:33], v[32:33], v[36:37]
	v_pk_mul_f32 v[42:43], v[42:43], v[48:49] op_sel_hi:[1,0]
	v_exp_f32_e32 v52, v52
	v_pk_fma_f32 v[44:45], v[50:51], v[44:45], v[50:51] op_sel_hi:[0,1,0]
	v_rcp_f32_e32 v44, v44
	v_rcp_f32_e32 v45, v45
	v_exp_f32_e32 v53, v53
	v_exp_f32_e32 v42, v42
	v_exp_f32_e32 v43, v43
	v_pk_mul_f32 v[36:37], v[32:33], v[44:45]
	v_pk_mul_f32 v[32:33], v[34:35], v[48:49] op_sel_hi:[1,0]
	v_pk_fma_f32 v[52:53], v[50:51], v[52:53], v[50:51] op_sel_hi:[0,1,0]
	v_exp_f32_e32 v32, v32
	v_exp_f32_e32 v33, v33
	v_pk_fma_f32 v[42:43], v[50:51], v[42:43], v[50:51] op_sel_hi:[0,1,0]
	v_rcp_f32_e32 v52, v52
; #define PG8_BAR __builtin_amdgcn_s_barrier()
; template <class Epi, class Sched, bool ALIGN_EPI = false, bool SP2 = false>
; __device__ __forceinline__ void gemm_phase(PG8_LAS unsigned char* lds, const Gemm g, const Sched& S, const Epi& E) {
;     ...
;         if (!has_next) break;
; #pragma unroll
;         for (int a = 0; a < 2; ++a)
; #pragma unroll
;             for (int b = 0; b < 2; ++b)
; #pragma unroll
;                 for (int m = 0; m < 4; ++m)
; #pragma unroll
;                     for (int n = 0; n < 2; ++n) acc[a][b][m][n] = (f32x4){0.f, 0.f, 0.f, 0.f};
;         cur = nxt; cA = nA; cB = nB; ++ui;
;         if constexpr (ALIGN_EPI) { if (wr == 1) PG8_BAR; }
;     __device__ __forceinline__ void operator()(const f32x4 (&acc)[2][2][4][2], const Unit& u, int wr, int wc, int fr, int fq, const LAS float* rt) const {
;     ...
;         for (int ai = 0; ai < 2; ++ai)
; #pragma unroll
;             for (int m = 0; m < 4; ++m) {
;                 const int row = row0 + ai * 128 + m * 16; const float rs = rsv[ai][m], nrs = -rs * LOG2E, irs2 = __builtin_amdgcn_rcpf(rs * rs);
;                 f32x4 o[2];
; #pragma unroll
;                 for (int n = 0; n < 2; ++n) {
;                     const f32x4 g = acc[ai][0][m][n], up = acc[ai][1][m][n];
; #pragma unroll
;                     for (int e = 0; e < 4; e += 2) {
;                         typedef float f32x2 __attribute__((ext_vector_type(2)));
;                         const f32x2 gg = (f32x2){g[e], g[e + 1]}, uu = (f32x2){up[e], up[e + 1]};
;                         const f32x2 t = gg * nrs;
;                         f32x2 ex; ex.x = __builtin_amdgcn_exp2f(t.x); ex.y = __builtin_amdgcn_exp2f(t.y);
;                         const f32x2 d = ex * irs2 + irs2;
;                         f32x2 r; r.x = __builtin_amdgcn_rcpf(d.x); r.y = __builtin_amdgcn_rcpf(d.y);
;                         const f32x2 oo = (gg * uu) * r; o[n][e] = oo.x; o[n][e + 1] = oo.y; }
;                 }
;                 gst<u32x4>(Ob + (size_t)row * 64, pack8(o[0], o[1]));
	v_rcp_f32_e32 v53, v53
	v_pk_fma_f32 v[32:33], v[50:51], v[32:33], v[50:51] op_sel_hi:[0,1,0]
	v_rcp_f32_e32 v42, v42
	v_rcp_f32_e32 v43, v43
	v_rcp_f32_e32 v32, v32
	v_rcp_f32_e32 v33, v33
	s_movk_i32 s0, 0x4000
	v_pk_mul_f32 v[40:41], v[40:41], v[52:53]
	v_pk_mul_f32 v[42:43], v[46:47], v[42:43]
	v_pk_mul_f32 v[38:39], v[38:39], v[32:33]
	v_cvt_pk_bf16_f32 v32, v40, v41
	v_cvt_pk_bf16_f32 v33, v42, v43
	v_cvt_pk_bf16_f32 v34, v36, v37
	v_add_co_u32_e32 v36, vcc, s0, v114
	v_cvt_pk_bf16_f32 v35, v38, v39
	v_pk_mul_f32 v[30:31], v[26:27], v[30:31]
	s_nop 0
	v_addc_co_u32_e32 v37, vcc, 0, v115, vcc
	global_store_dwordx4 v[36:37], v[32:35], off offset:2048 nt
	v_pk_mul_f32 v[22:23], v[18:19], v[22:23]
	s_movk_i32 s0, 0x5000
	v_mul_f32_e32 v32, 0xbfb8aa3b, v158
	v_mul_f32_e32 v33, v158, v158
	v_pk_mul_f32 v[36:37], v[24:25], v[32:33] op_sel_hi:[1,0]
	v_pk_mul_f32 v[24:25], v[24:25], v[28:29]
	v_pk_mul_f32 v[28:29], v[16:17], v[32:33] op_sel_hi:[1,0]
	v_rcp_f32_e32 v34, v33
	v_exp_f32_e32 v28, v28
	v_exp_f32_e32 v29, v29
	v_pk_mul_f32 v[16:17], v[16:17], v[20:21]
	v_pk_mul_f32 v[26:27], v[26:27], v[32:33] op_sel_hi:[1,0]
	v_exp_f32_e32 v36, v36
	v_pk_fma_f32 v[28:29], v[34:35], v[28:29], v[34:35] op_sel_hi:[0,1,0]
	v_rcp_f32_e32 v28, v28
	v_rcp_f32_e32 v29, v29
	v_exp_f32_e32 v37, v37
	v_exp_f32_e32 v26, v26
	v_exp_f32_e32 v27, v27
	v_pk_mul_f32 v[20:21], v[16:17], v[28:29]
	v_pk_mul_f32 v[16:17], v[18:19], v[32:33] op_sel_hi:[1,0]
	v_pk_fma_f32 v[36:37], v[34:35], v[36:37], v[34:35] op_sel_hi:[0,1,0]
	v_exp_f32_e32 v16, v16
	v_exp_f32_e32 v17, v17
	v_pk_fma_f32 v[26:27], v[34:35], v[26:27], v[34:35] op_sel_hi:[0,1,0]
	v_rcp_f32_e32 v36, v36
	v_rcp_f32_e32 v37, v37
	v_pk_fma_f32 v[16:17], v[34:35], v[16:17], v[34:35] op_sel_hi:[0,1,0]
	v_rcp_f32_e32 v26, v26
	v_rcp_f32_e32 v27, v27
	v_rcp_f32_e32 v16, v16
	v_rcp_f32_e32 v17, v17
	v_pk_mul_f32 v[24:25], v[24:25], v[36:37]
	v_pk_mul_f32 v[26:27], v[30:31], v[26:27]
	v_pk_mul_f32 v[14:15], v[10:11], v[14:15]
	v_pk_mul_f32 v[22:23], v[22:23], v[16:17]
	v_cvt_pk_bf16_f32 v16, v24, v25
	v_cvt_pk_bf16_f32 v17, v26, v27
	v_cvt_pk_bf16_f32 v18, v20, v21
	v_add_co_u32_e32 v20, vcc, s0, v114
	v_cvt_pk_bf16_f32 v19, v22, v23
	v_pk_mul_f32 v[6:7], v[2:3], v[6:7]
	s_nop 0
	v_addc_co_u32_e32 v21, vcc, 0, v115, vcc
	global_store_dwordx4 v[20:21], v[16:19], off nt
	s_mov_b64 s[0:1], -1
	s_andn2_b64 vcc, exec, s[40:41]
	v_mul_f32_e32 v16, 0xbfb8aa3b, v157
	v_mul_f32_e32 v17, v157, v157
	v_pk_mul_f32 v[20:21], v[8:9], v[16:17] op_sel_hi:[1,0]
	v_pk_mul_f32 v[8:9], v[8:9], v[12:13]
	v_pk_mul_f32 v[12:13], v[0:1], v[16:17] op_sel_hi:[1,0]
	v_rcp_f32_e32 v18, v17
	v_exp_f32_e32 v12, v12
	v_exp_f32_e32 v13, v13
	v_pk_mul_f32 v[0:1], v[0:1], v[4:5]
	v_pk_mul_f32 v[10:11], v[10:11], v[16:17] op_sel_hi:[1,0]
	v_exp_f32_e32 v20, v20
	v_pk_fma_f32 v[12:13], v[18:19], v[12:13], v[18:19] op_sel_hi:[0,1,0]
	v_rcp_f32_e32 v12, v12
	v_rcp_f32_e32 v13, v13
	v_exp_f32_e32 v21, v21
	v_exp_f32_e32 v10, v10
	v_exp_f32_e32 v11, v11
	v_pk_mul_f32 v[4:5], v[0:1], v[12:13]
	v_pk_mul_f32 v[0:1], v[2:3], v[16:17] op_sel_hi:[1,0]
	v_pk_fma_f32 v[20:21], v[18:19], v[20:21], v[18:19] op_sel_hi:[0,1,0]
	v_exp_f32_e32 v0, v0
	v_exp_f32_e32 v1, v1
	v_pk_fma_f32 v[10:11], v[18:19], v[10:11], v[18:19] op_sel_hi:[0,1,0]
	v_rcp_f32_e32 v20, v20
	v_rcp_f32_e32 v21, v21
	v_pk_fma_f32 v[0:1], v[18:19], v[0:1], v[18:19] op_sel_hi:[0,1,0]
	v_rcp_f32_e32 v0, v0
	v_rcp_f32_e32 v1, v1
	v_rcp_f32_e32 v10, v10
	v_rcp_f32_e32 v11, v11
	v_pk_mul_f32 v[8:9], v[8:9], v[20:21]
	v_pk_mul_f32 v[6:7], v[6:7], v[0:1]
	v_lshlrev_b64 v[0:1], 7, v[142:143]
	v_lshl_add_u64 v[12:13], v[144:145], 0, v[0:1]
	v_pk_mul_f32 v[10:11], v[14:15], v[10:11]
	v_cvt_pk_bf16_f32 v0, v8, v9
	s_nop 0
	v_cvt_pk_bf16_f32 v1, v10, v11
	v_cvt_pk_bf16_f32 v2, v4, v5
	v_cvt_pk_bf16_f32 v3, v6, v7
	global_store_dwordx4 v[12:13], v[0:3], off nt
	s_cbranch_vccnz .LBB0_474
	v_readlane_b32 s0, v255, 7
	v_readlane_b32 s1, v255, 8
	s_andn2_b64 vcc, exec, s[0:1]
	s_cbranch_vccnz .LBB0_473
	s_barrier
	s_branch .LBB0_473
